# conv row prefetch depth 6 (with the non-temporal loads)
# baseline (speedup 1.0000x reference)
; __device__ __forceinline__ unsigned cvt_pk_bf16(float lo, float hi) { unsigned r; asm volatile("v_cvt_pk_bf16_f32 %0, %1, %2" : "=v"(r) : "v"(lo), "v"(hi)); return r; }
; __device__ __forceinline__ float bf_lo(unsigned w) { return __uint_as_float(w << 16); }
; __device__ __forceinline__ float bf_hi(unsigned w) { return __uint_as_float(w & 0xffff0000u); }
; __global__ void __launch_bounds__(512, 2) trunk_fwd(Args args) {
;     ...
;                 for (int rr = 0; rr < 16; ++rr) {
;                     const int r = r0 + rr;
;                     const u32x4 gb = gb_n, gu = gu_n; const f32x4 pv4 = pv_n;
;                     if (rr < 15) { gb_n = *(const u32x4*)(Z + (size_t)(r + 1) * INP + 768 + c0); gu_n = *(const u32x4*)(Z + (size_t)(r + 1) * INP + 1280 + c0);
;                                    pv_n = *(const f32x4*)(pl + (size_t)(r + 1) * PLE + lane * 4); }
;                     float cv[8], uu[8]; float ss = 0.f;
; #pragma unroll
;                     for (int i = 0; i < 4; ++i) {
;                         uu[2 * i] = bf_lo(gu[i]); uu[2 * i + 1] = bf_hi(gu[i]);
;                         cv[2 * i] = bf_lo(gb[i]) * (w0[2 * i] * uu[2 * i] + w1[2 * i] * u1[2 * i] + w2[2 * i] * u2[2 * i]);
;                         cv[2 * i + 1] = bf_hi(gb[i]) * (w0[2 * i + 1] * uu[2 * i + 1] + w1[2 * i + 1] * u1[2 * i + 1] + w2[2 * i + 1] * u2[2 * i + 1]);
;                     }
; #pragma unroll
;                     for (int i = 0; i < 8; ++i) { ss += cv[i] * cv[i]; u2[i] = u1[i]; u1[i] = uu[i]; }
;                     ss = wave_sum(ss);
;                     const float rc = rsqrtf(ss * (1.0f / 512.0f) + EPS);
;                     u32x4 oc;
; #pragma unroll
;                     for (int i = 0; i < 4; ++i) oc[i] = cvt_pk_bf16(cv[2 * i] * rc, cv[2 * i + 1] * rc);
;                     *(u32x4*)(MIX + (size_t)r * 1024 + 512 + c0) = oc;
;                     u32x2 pw; pw.x = cvt_pk_bf16(pv4[0], pv4[1]); pw.y = cvt_pk_bf16(pv4[2], pv4[3]);
;                     *(u32x2*)(PB + (size_t)r * PLE + lane * 4) = pw;
;                 }
.Lcv_taps_ok:
	v_mad_i64_i32 v[152:153], vcc, s41, v221, v[58:59]
	s_add_u32 s41, s41, 1
	global_load_dwordx4 v[2:5], v[152:153], off offset:1536 nt
	global_load_dwordx4 v[18:21], v[152:153], off offset:2560 nt
	v_mad_i64_i32 v[152:153], vcc, s41, v221, v[58:59]
	s_add_u32 s41, s41, 1
	global_load_dwordx4 v[6:9], v[152:153], off offset:1536 nt
	global_load_dwordx4 v[22:25], v[152:153], off offset:2560 nt
	v_mad_i64_i32 v[152:153], vcc, s41, v221, v[58:59]
	s_add_u32 s41, s41, 1
	global_load_dwordx4 v[10:13], v[152:153], off offset:1536 nt
	global_load_dwordx4 v[26:29], v[152:153], off offset:2560 nt
	v_mad_i64_i32 v[152:153], vcc, s41, v221, v[58:59]
	s_add_u32 s41, s41, 1
	global_load_dwordx4 v[14:17], v[152:153], off offset:1536 nt
	global_load_dwordx4 v[30:33], v[152:153], off offset:2560 nt
	v_mad_i64_i32 v[152:153], vcc, s41, v221, v[58:59]
	s_add_u32 s41, s41, 1
	global_load_dwordx4 v[34:37], v[152:153], off offset:1536 nt
	global_load_dwordx4 v[60:63], v[152:153], off offset:2560 nt
	v_mad_i64_i32 v[152:153], vcc, s41, v221, v[58:59]
	s_add_u32 s41, s41, 1
	global_load_dwordx4 v[38:41], v[152:153], off offset:1536 nt
	global_load_dwordx4 v[64:67], v[152:153], off offset:2560 nt
	s_waitcnt vmcnt(10)
	v_lshlrev_b32_e32 v188, 16, v18
	v_and_b32_e32 v189, 0xffff0000, v18
	v_lshlrev_b32_e32 v190, 16, v19
	v_and_b32_e32 v191, 0xffff0000, v19
	v_lshlrev_b32_e32 v192, 16, v20
	v_and_b32_e32 v193, 0xffff0000, v20
	v_lshlrev_b32_e32 v194, 16, v21
	v_and_b32_e32 v195, 0xffff0000, v21
	v_mul_f32_e32 v140, v164, v188
	v_mul_f32_e32 v141, v165, v189
	v_mul_f32_e32 v142, v166, v190
	v_mul_f32_e32 v143, v167, v191
	v_mul_f32_e32 v144, v168, v192
	v_mul_f32_e32 v145, v169, v193
	v_mul_f32_e32 v146, v170, v194
	v_mul_f32_e32 v147, v171, v195
	v_fmac_f32_e32 v140, v172, v204
	v_fmac_f32_e32 v141, v173, v205
	v_fmac_f32_e32 v142, v174, v206
	v_fmac_f32_e32 v143, v175, v207
	v_fmac_f32_e32 v144, v176, v208
	v_fmac_f32_e32 v145, v177, v209
	v_fmac_f32_e32 v146, v178, v210
	v_fmac_f32_e32 v147, v179, v211
	v_fmac_f32_e32 v140, v180, v196
	v_fmac_f32_e32 v141, v181, v197
	v_fmac_f32_e32 v142, v182, v198
	v_fmac_f32_e32 v143, v183, v199
	v_fmac_f32_e32 v144, v184, v200
	v_fmac_f32_e32 v145, v185, v201
	v_fmac_f32_e32 v146, v186, v202
	v_fmac_f32_e32 v147, v187, v203
	v_lshlrev_b32_e32 v150, 16, v2
	v_and_b32_e32 v151, 0xffff0000, v2
	v_mul_f32_e32 v140, v150, v140
	v_mul_f32_e32 v141, v151, v141
	v_lshlrev_b32_e32 v150, 16, v3
	v_and_b32_e32 v151, 0xffff0000, v3
	v_mul_f32_e32 v142, v150, v142
	v_mul_f32_e32 v143, v151, v143
	v_lshlrev_b32_e32 v150, 16, v4
	v_and_b32_e32 v151, 0xffff0000, v4
	v_mul_f32_e32 v144, v150, v144
	v_mul_f32_e32 v145, v151, v145
	v_lshlrev_b32_e32 v150, 16, v5
	v_and_b32_e32 v151, 0xffff0000, v5
	v_mul_f32_e32 v146, v150, v146
	v_mul_f32_e32 v147, v151, v147
	v_mul_f32_e32 v148, v140, v140
	v_fmac_f32_e32 v148, v141, v141
	v_fmac_f32_e32 v148, v142, v142
	v_fmac_f32_e32 v148, v143, v143
	v_fmac_f32_e32 v148, v144, v144
	v_fmac_f32_e32 v148, v145, v145
	v_fmac_f32_e32 v148, v146, v146
	v_fmac_f32_e32 v148, v147, v147
	v_mad_i64_i32 v[152:153], vcc, s41, v221, v[58:59]
	s_add_u32 s41, s41, 1
	global_load_dwordx4 v[2:5], v[152:153], off offset:1536 nt
	global_load_dwordx4 v[18:21], v[152:153], off offset:2560 nt
	s_nop 1
	v_add_f32_dpp v148, v148, v148 quad_perm:[1,0,3,2] row_mask:0xf bank_mask:0xf
	s_nop 1
	v_add_f32_dpp v148, v148, v148 quad_perm:[2,3,0,1] row_mask:0xf bank_mask:0xf
	s_nop 1
	v_add_f32_dpp v148, v148, v148 row_half_mirror row_mask:0xf bank_mask:0xf
	s_nop 1
	v_add_f32_dpp v148, v148, v148 row_mirror row_mask:0xf bank_mask:0xf
	s_nop 1
	v_add_f32_dpp v148, v148, v148 row_bcast:15 row_mask:0xa bank_mask:0xf
	s_nop 1
	v_add_f32_dpp v148, v148, v148 row_bcast:31 row_mask:0xc bank_mask:0xf
	s_nop 0
	v_readlane_b32 s0, v148, 63
	s_nop 1
	v_mov_b32_e32 v148, s0
	v_fmamk_f32 v148, v148, 0x3b000000, v162
	v_mul_f32_e32 v150, 0x4b800000, v148
	v_cmp_gt_f32_e32 vcc, s31, v148
	s_nop 1
	v_cndmask_b32_e32 v148, v148, v150, vcc
	v_rsq_f32_e32 v148, v148
	s_nop 0
	v_mul_f32_e32 v150, 0x45800000, v148
	v_cndmask_b32_e32 v149, v148, v150, vcc
	v_mul_f32_e32 v140, v149, v140
	v_mul_f32_e32 v141, v149, v141
	v_mul_f32_e32 v142, v149, v142
	v_mul_f32_e32 v143, v149, v143
	v_mul_f32_e32 v144, v149, v144
	v_mul_f32_e32 v145, v149, v145
	v_mul_f32_e32 v146, v149, v146
	v_mul_f32_e32 v147, v149, v147
	v_cvt_pk_bf16_f32 v140, v140, v141
	v_cvt_pk_bf16_f32 v141, v142, v143
	v_cvt_pk_bf16_f32 v142, v144, v145
	v_cvt_pk_bf16_f32 v143, v146, v147
	global_store_dwordx4 v[156:157], v[140:143], off sc1
	s_waitcnt vmcnt(11)
; __device__ __forceinline__ unsigned cvt_pk_bf16(float lo, float hi) { unsigned r; asm volatile("v_cvt_pk_bf16_f32 %0, %1, %2" : "=v"(r) : "v"(lo), "v"(hi)); return r; }
; __device__ __forceinline__ float bf_lo(unsigned w) { return __uint_as_float(w << 16); }
; __device__ __forceinline__ float bf_hi(unsigned w) { return __uint_as_float(w & 0xffff0000u); }
; __global__ void __launch_bounds__(512, 2) trunk_fwd(Args args) {
;     ...
;                 for (int rr = 0; rr < 16; ++rr) {
;                     const int r = r0 + rr;
;                     const u32x4 gb = gb_n, gu = gu_n; const f32x4 pv4 = pv_n;
;                     if (rr < 15) { gb_n = *(const u32x4*)(Z + (size_t)(r + 1) * INP + 768 + c0); gu_n = *(const u32x4*)(Z + (size_t)(r + 1) * INP + 1280 + c0);
;                                    pv_n = *(const f32x4*)(pl + (size_t)(r + 1) * PLE + lane * 4); }
;                     float cv[8], uu[8]; float ss = 0.f;
; #pragma unroll
;                     for (int i = 0; i < 4; ++i) {
;                         uu[2 * i] = bf_lo(gu[i]); uu[2 * i + 1] = bf_hi(gu[i]);
;                         cv[2 * i] = bf_lo(gb[i]) * (w0[2 * i] * uu[2 * i] + w1[2 * i] * u1[2 * i] + w2[2 * i] * u2[2 * i]);
;                         cv[2 * i + 1] = bf_hi(gb[i]) * (w0[2 * i + 1] * uu[2 * i + 1] + w1[2 * i + 1] * u1[2 * i + 1] + w2[2 * i + 1] * u2[2 * i + 1]);
;                     }
; #pragma unroll
;                     for (int i = 0; i < 8; ++i) { ss += cv[i] * cv[i]; u2[i] = u1[i]; u1[i] = uu[i]; }
;                     ss = wave_sum(ss);
;                     const float rc = rsqrtf(ss * (1.0f / 512.0f) + EPS);
;                     u32x4 oc;
; #pragma unroll
;                     for (int i = 0; i < 4; ++i) oc[i] = cvt_pk_bf16(cv[2 * i] * rc, cv[2 * i + 1] * rc);
;                     *(u32x4*)(MIX + (size_t)r * 1024 + 512 + c0) = oc;
	v_lshlrev_b32_e32 v196, 16, v22
	v_and_b32_e32 v197, 0xffff0000, v22
	v_lshlrev_b32_e32 v198, 16, v23
	v_and_b32_e32 v199, 0xffff0000, v23
	v_lshlrev_b32_e32 v200, 16, v24
	v_and_b32_e32 v201, 0xffff0000, v24
	v_lshlrev_b32_e32 v202, 16, v25
	v_and_b32_e32 v203, 0xffff0000, v25
	v_mul_f32_e32 v140, v164, v196
	v_mul_f32_e32 v141, v165, v197
	v_mul_f32_e32 v142, v166, v198
	v_mul_f32_e32 v143, v167, v199
	v_mul_f32_e32 v144, v168, v200
	v_mul_f32_e32 v145, v169, v201
	v_mul_f32_e32 v146, v170, v202
	v_mul_f32_e32 v147, v171, v203
	v_fmac_f32_e32 v140, v172, v188
	v_fmac_f32_e32 v141, v173, v189
	v_fmac_f32_e32 v142, v174, v190
	v_fmac_f32_e32 v143, v175, v191
	v_fmac_f32_e32 v144, v176, v192
	v_fmac_f32_e32 v145, v177, v193
	v_fmac_f32_e32 v146, v178, v194
	v_fmac_f32_e32 v147, v179, v195
	v_fmac_f32_e32 v140, v180, v204
	v_fmac_f32_e32 v141, v181, v205
	v_fmac_f32_e32 v142, v182, v206
	v_fmac_f32_e32 v143, v183, v207
	v_fmac_f32_e32 v144, v184, v208
	v_fmac_f32_e32 v145, v185, v209
	v_fmac_f32_e32 v146, v186, v210
	v_fmac_f32_e32 v147, v187, v211
	v_lshlrev_b32_e32 v150, 16, v6
	v_and_b32_e32 v151, 0xffff0000, v6
	v_mul_f32_e32 v140, v150, v140
	v_mul_f32_e32 v141, v151, v141
	v_lshlrev_b32_e32 v150, 16, v7
	v_and_b32_e32 v151, 0xffff0000, v7
	v_mul_f32_e32 v142, v150, v142
	v_mul_f32_e32 v143, v151, v143
	v_lshlrev_b32_e32 v150, 16, v8
	v_and_b32_e32 v151, 0xffff0000, v8
	v_mul_f32_e32 v144, v150, v144
	v_mul_f32_e32 v145, v151, v145
	v_lshlrev_b32_e32 v150, 16, v9
	v_and_b32_e32 v151, 0xffff0000, v9
	v_mul_f32_e32 v146, v150, v146
	v_mul_f32_e32 v147, v151, v147
	v_mul_f32_e32 v148, v140, v140
	v_fmac_f32_e32 v148, v141, v141
	v_fmac_f32_e32 v148, v142, v142
	v_fmac_f32_e32 v148, v143, v143
	v_fmac_f32_e32 v148, v144, v144
	v_fmac_f32_e32 v148, v145, v145
	v_fmac_f32_e32 v148, v146, v146
	v_fmac_f32_e32 v148, v147, v147
	v_mad_i64_i32 v[152:153], vcc, s41, v221, v[58:59]
	s_add_u32 s41, s41, 1
	global_load_dwordx4 v[6:9], v[152:153], off offset:1536 nt
	global_load_dwordx4 v[22:25], v[152:153], off offset:2560 nt
	s_nop 1
	v_add_f32_dpp v148, v148, v148 quad_perm:[1,0,3,2] row_mask:0xf bank_mask:0xf
	s_nop 1
	v_add_f32_dpp v148, v148, v148 quad_perm:[2,3,0,1] row_mask:0xf bank_mask:0xf
	s_nop 1
	v_add_f32_dpp v148, v148, v148 row_half_mirror row_mask:0xf bank_mask:0xf
	s_nop 1
	v_add_f32_dpp v148, v148, v148 row_mirror row_mask:0xf bank_mask:0xf
	s_nop 1
	v_add_f32_dpp v148, v148, v148 row_bcast:15 row_mask:0xa bank_mask:0xf
	s_nop 1
	v_add_f32_dpp v148, v148, v148 row_bcast:31 row_mask:0xc bank_mask:0xf
	s_nop 0
	v_readlane_b32 s0, v148, 63
	s_nop 1
	v_mov_b32_e32 v148, s0
	v_fmamk_f32 v148, v148, 0x3b000000, v162
	v_mul_f32_e32 v150, 0x4b800000, v148
	v_cmp_gt_f32_e32 vcc, s31, v148
	s_nop 1
	v_cndmask_b32_e32 v148, v148, v150, vcc
	v_rsq_f32_e32 v148, v148
	s_nop 0
	v_mul_f32_e32 v150, 0x45800000, v148
	v_cndmask_b32_e32 v149, v148, v150, vcc
	v_mul_f32_e32 v140, v149, v140
	v_mul_f32_e32 v141, v149, v141
	v_mul_f32_e32 v142, v149, v142
	v_mul_f32_e32 v143, v149, v143
	v_mul_f32_e32 v144, v149, v144
	v_mul_f32_e32 v145, v149, v145
	v_mul_f32_e32 v146, v149, v146
	v_mul_f32_e32 v147, v149, v147
	v_cvt_pk_bf16_f32 v140, v140, v141
	v_cvt_pk_bf16_f32 v141, v142, v143
	v_cvt_pk_bf16_f32 v142, v144, v145
	v_cvt_pk_bf16_f32 v143, v146, v147
	global_store_dwordx4 v[156:157], v[140:143], off offset:2048 sc1
	v_lshl_add_u64 v[156:157], v[156:157], 0, s[20:21]
	s_waitcnt vmcnt(12)
	v_lshlrev_b32_e32 v204, 16, v26
	v_and_b32_e32 v205, 0xffff0000, v26
	v_lshlrev_b32_e32 v206, 16, v27
	v_and_b32_e32 v207, 0xffff0000, v27
	v_lshlrev_b32_e32 v208, 16, v28
	v_and_b32_e32 v209, 0xffff0000, v28
	v_lshlrev_b32_e32 v210, 16, v29
	v_and_b32_e32 v211, 0xffff0000, v29
	v_mul_f32_e32 v140, v164, v204
	v_mul_f32_e32 v141, v165, v205
	v_mul_f32_e32 v142, v166, v206
	v_mul_f32_e32 v143, v167, v207
	v_mul_f32_e32 v144, v168, v208
	v_mul_f32_e32 v145, v169, v209
	v_mul_f32_e32 v146, v170, v210
	v_mul_f32_e32 v147, v171, v211
	v_fmac_f32_e32 v140, v172, v196
	v_fmac_f32_e32 v141, v173, v197
	v_fmac_f32_e32 v142, v174, v198
	v_fmac_f32_e32 v143, v175, v199
	v_fmac_f32_e32 v144, v176, v200
	v_fmac_f32_e32 v145, v177, v201
	v_fmac_f32_e32 v146, v178, v202
	v_fmac_f32_e32 v147, v179, v203
	v_fmac_f32_e32 v140, v180, v188
	v_fmac_f32_e32 v141, v181, v189
	v_fmac_f32_e32 v142, v182, v190
	v_fmac_f32_e32 v143, v183, v191
	v_fmac_f32_e32 v144, v184, v192
	v_fmac_f32_e32 v145, v185, v193
	v_fmac_f32_e32 v146, v186, v194
	v_fmac_f32_e32 v147, v187, v195
	v_lshlrev_b32_e32 v150, 16, v10
	v_and_b32_e32 v151, 0xffff0000, v10
	v_mul_f32_e32 v140, v150, v140
	v_mul_f32_e32 v141, v151, v141
	v_lshlrev_b32_e32 v150, 16, v11
	v_and_b32_e32 v151, 0xffff0000, v11
	v_mul_f32_e32 v142, v150, v142
	v_mul_f32_e32 v143, v151, v143
	v_lshlrev_b32_e32 v150, 16, v12
	v_and_b32_e32 v151, 0xffff0000, v12
	v_mul_f32_e32 v144, v150, v144
	v_mul_f32_e32 v145, v151, v145
	v_lshlrev_b32_e32 v150, 16, v13
	v_and_b32_e32 v151, 0xffff0000, v13
	v_mul_f32_e32 v146, v150, v146
	v_mul_f32_e32 v147, v151, v147
	v_mul_f32_e32 v148, v140, v140
	v_fmac_f32_e32 v148, v141, v141
	v_fmac_f32_e32 v148, v142, v142
	v_fmac_f32_e32 v148, v143, v143
	v_fmac_f32_e32 v148, v144, v144
	v_fmac_f32_e32 v148, v145, v145
	v_fmac_f32_e32 v148, v146, v146
	v_fmac_f32_e32 v148, v147, v147
	v_mad_i64_i32 v[152:153], vcc, s41, v221, v[58:59]
	s_add_u32 s41, s41, 1
	global_load_dwordx4 v[10:13], v[152:153], off offset:1536 nt
	global_load_dwordx4 v[26:29], v[152:153], off offset:2560 nt
	s_nop 1
	v_add_f32_dpp v148, v148, v148 quad_perm:[1,0,3,2] row_mask:0xf bank_mask:0xf
	s_nop 1
	v_add_f32_dpp v148, v148, v148 quad_perm:[2,3,0,1] row_mask:0xf bank_mask:0xf
	s_nop 1
	v_add_f32_dpp v148, v148, v148 row_half_mirror row_mask:0xf bank_mask:0xf
	s_nop 1
	v_add_f32_dpp v148, v148, v148 row_mirror row_mask:0xf bank_mask:0xf
	s_nop 1
	v_add_f32_dpp v148, v148, v148 row_bcast:15 row_mask:0xa bank_mask:0xf
	s_nop 1
	v_add_f32_dpp v148, v148, v148 row_bcast:31 row_mask:0xc bank_mask:0xf
	s_nop 0
	v_readlane_b32 s0, v148, 63
	s_nop 1
	v_mov_b32_e32 v148, s0
	v_fmamk_f32 v148, v148, 0x3b000000, v162
	v_mul_f32_e32 v150, 0x4b800000, v148
	v_cmp_gt_f32_e32 vcc, s31, v148
	s_nop 1
	v_cndmask_b32_e32 v148, v148, v150, vcc
	v_rsq_f32_e32 v148, v148
	s_nop 0
	v_mul_f32_e32 v150, 0x45800000, v148
	v_cndmask_b32_e32 v149, v148, v150, vcc
	v_mul_f32_e32 v140, v149, v140
	v_mul_f32_e32 v141, v149, v141
	v_mul_f32_e32 v142, v149, v142
	v_mul_f32_e32 v143, v149, v143
	v_mul_f32_e32 v144, v149, v144
	v_mul_f32_e32 v145, v149, v145
	v_mul_f32_e32 v146, v149, v146
	v_mul_f32_e32 v147, v149, v147
	v_cvt_pk_bf16_f32 v140, v140, v141
	v_cvt_pk_bf16_f32 v141, v142, v143
	v_cvt_pk_bf16_f32 v142, v144, v145
	v_cvt_pk_bf16_f32 v143, v146, v147
	global_store_dwordx4 v[156:157], v[140:143], off sc1
	s_waitcnt vmcnt(13)
; __device__ __forceinline__ unsigned cvt_pk_bf16(float lo, float hi) { unsigned r; asm volatile("v_cvt_pk_bf16_f32 %0, %1, %2" : "=v"(r) : "v"(lo), "v"(hi)); return r; }
; __device__ __forceinline__ float bf_lo(unsigned w) { return __uint_as_float(w << 16); }
; __device__ __forceinline__ float bf_hi(unsigned w) { return __uint_as_float(w & 0xffff0000u); }
; __global__ void __launch_bounds__(512, 2) trunk_fwd(Args args) {
;     ...
;                 for (int rr = 0; rr < 16; ++rr) {
;                     const int r = r0 + rr;
;                     const u32x4 gb = gb_n, gu = gu_n; const f32x4 pv4 = pv_n;
;                     if (rr < 15) { gb_n = *(const u32x4*)(Z + (size_t)(r + 1) * INP + 768 + c0); gu_n = *(const u32x4*)(Z + (size_t)(r + 1) * INP + 1280 + c0);
;                                    pv_n = *(const f32x4*)(pl + (size_t)(r + 1) * PLE + lane * 4); }
;                     float cv[8], uu[8]; float ss = 0.f;
; #pragma unroll
;                     for (int i = 0; i < 4; ++i) {
;                         uu[2 * i] = bf_lo(gu[i]); uu[2 * i + 1] = bf_hi(gu[i]);
;                         cv[2 * i] = bf_lo(gb[i]) * (w0[2 * i] * uu[2 * i] + w1[2 * i] * u1[2 * i] + w2[2 * i] * u2[2 * i]);
;                         cv[2 * i + 1] = bf_hi(gb[i]) * (w0[2 * i + 1] * uu[2 * i + 1] + w1[2 * i + 1] * u1[2 * i + 1] + w2[2 * i + 1] * u2[2 * i + 1]);
;                     }
; #pragma unroll
;                     for (int i = 0; i < 8; ++i) { ss += cv[i] * cv[i]; u2[i] = u1[i]; u1[i] = uu[i]; }
;                     ss = wave_sum(ss);
;                     const float rc = rsqrtf(ss * (1.0f / 512.0f) + EPS);
;                     u32x4 oc;
; #pragma unroll
;                     for (int i = 0; i < 4; ++i) oc[i] = cvt_pk_bf16(cv[2 * i] * rc, cv[2 * i + 1] * rc);
;                     *(u32x4*)(MIX + (size_t)r * 1024 + 512 + c0) = oc;
	v_lshlrev_b32_e32 v188, 16, v30
	v_and_b32_e32 v189, 0xffff0000, v30
	v_lshlrev_b32_e32 v190, 16, v31
	v_and_b32_e32 v191, 0xffff0000, v31
	v_lshlrev_b32_e32 v192, 16, v32
	v_and_b32_e32 v193, 0xffff0000, v32
	v_lshlrev_b32_e32 v194, 16, v33
	v_and_b32_e32 v195, 0xffff0000, v33
	v_mul_f32_e32 v140, v164, v188
	v_mul_f32_e32 v141, v165, v189
	v_mul_f32_e32 v142, v166, v190
	v_mul_f32_e32 v143, v167, v191
	v_mul_f32_e32 v144, v168, v192
	v_mul_f32_e32 v145, v169, v193
	v_mul_f32_e32 v146, v170, v194
	v_mul_f32_e32 v147, v171, v195
	v_fmac_f32_e32 v140, v172, v204
	v_fmac_f32_e32 v141, v173, v205
	v_fmac_f32_e32 v142, v174, v206
	v_fmac_f32_e32 v143, v175, v207
	v_fmac_f32_e32 v144, v176, v208
	v_fmac_f32_e32 v145, v177, v209
	v_fmac_f32_e32 v146, v178, v210
	v_fmac_f32_e32 v147, v179, v211
	v_fmac_f32_e32 v140, v180, v196
	v_fmac_f32_e32 v141, v181, v197
	v_fmac_f32_e32 v142, v182, v198
	v_fmac_f32_e32 v143, v183, v199
	v_fmac_f32_e32 v144, v184, v200
	v_fmac_f32_e32 v145, v185, v201
	v_fmac_f32_e32 v146, v186, v202
	v_fmac_f32_e32 v147, v187, v203
	v_lshlrev_b32_e32 v150, 16, v14
	v_and_b32_e32 v151, 0xffff0000, v14
	v_mul_f32_e32 v140, v150, v140
	v_mul_f32_e32 v141, v151, v141
	v_lshlrev_b32_e32 v150, 16, v15
	v_and_b32_e32 v151, 0xffff0000, v15
	v_mul_f32_e32 v142, v150, v142
	v_mul_f32_e32 v143, v151, v143
	v_lshlrev_b32_e32 v150, 16, v16
	v_and_b32_e32 v151, 0xffff0000, v16
	v_mul_f32_e32 v144, v150, v144
	v_mul_f32_e32 v145, v151, v145
	v_lshlrev_b32_e32 v150, 16, v17
	v_and_b32_e32 v151, 0xffff0000, v17
	v_mul_f32_e32 v146, v150, v146
	v_mul_f32_e32 v147, v151, v147
	v_mul_f32_e32 v148, v140, v140
	v_fmac_f32_e32 v148, v141, v141
	v_fmac_f32_e32 v148, v142, v142
	v_fmac_f32_e32 v148, v143, v143
	v_fmac_f32_e32 v148, v144, v144
	v_fmac_f32_e32 v148, v145, v145
	v_fmac_f32_e32 v148, v146, v146
	v_fmac_f32_e32 v148, v147, v147
	v_mad_i64_i32 v[152:153], vcc, s41, v221, v[58:59]
	s_add_u32 s41, s41, 1
	global_load_dwordx4 v[14:17], v[152:153], off offset:1536 nt
	global_load_dwordx4 v[30:33], v[152:153], off offset:2560 nt
	s_nop 1
	v_add_f32_dpp v148, v148, v148 quad_perm:[1,0,3,2] row_mask:0xf bank_mask:0xf
	s_nop 1
	v_add_f32_dpp v148, v148, v148 quad_perm:[2,3,0,1] row_mask:0xf bank_mask:0xf
	s_nop 1
	v_add_f32_dpp v148, v148, v148 row_half_mirror row_mask:0xf bank_mask:0xf
	s_nop 1
	v_add_f32_dpp v148, v148, v148 row_mirror row_mask:0xf bank_mask:0xf
	s_nop 1
	v_add_f32_dpp v148, v148, v148 row_bcast:15 row_mask:0xa bank_mask:0xf
	s_nop 1
	v_add_f32_dpp v148, v148, v148 row_bcast:31 row_mask:0xc bank_mask:0xf
	s_nop 0
	v_readlane_b32 s0, v148, 63
	s_nop 1
	v_mov_b32_e32 v148, s0
	v_fmamk_f32 v148, v148, 0x3b000000, v162
	v_mul_f32_e32 v150, 0x4b800000, v148
	v_cmp_gt_f32_e32 vcc, s31, v148
	s_nop 1
	v_cndmask_b32_e32 v148, v148, v150, vcc
	v_rsq_f32_e32 v148, v148
	s_nop 0
	v_mul_f32_e32 v150, 0x45800000, v148
	v_cndmask_b32_e32 v149, v148, v150, vcc
	v_mul_f32_e32 v140, v149, v140
	v_mul_f32_e32 v141, v149, v141
	v_mul_f32_e32 v142, v149, v142
	v_mul_f32_e32 v143, v149, v143
	v_mul_f32_e32 v144, v149, v144
	v_mul_f32_e32 v145, v149, v145
	v_mul_f32_e32 v146, v149, v146
	v_mul_f32_e32 v147, v149, v147
	v_cvt_pk_bf16_f32 v140, v140, v141
	v_cvt_pk_bf16_f32 v141, v142, v143
	v_cvt_pk_bf16_f32 v142, v144, v145
	v_cvt_pk_bf16_f32 v143, v146, v147
	global_store_dwordx4 v[156:157], v[140:143], off offset:2048 sc1
	v_lshl_add_u64 v[156:157], v[156:157], 0, s[20:21]
	s_waitcnt vmcnt(14)
	v_lshlrev_b32_e32 v196, 16, v60
	v_and_b32_e32 v197, 0xffff0000, v60
	v_lshlrev_b32_e32 v198, 16, v61
	v_and_b32_e32 v199, 0xffff0000, v61
	v_lshlrev_b32_e32 v200, 16, v62
	v_and_b32_e32 v201, 0xffff0000, v62
	v_lshlrev_b32_e32 v202, 16, v63
	v_and_b32_e32 v203, 0xffff0000, v63
	v_mul_f32_e32 v140, v164, v196
	v_mul_f32_e32 v141, v165, v197
	v_mul_f32_e32 v142, v166, v198
	v_mul_f32_e32 v143, v167, v199
	v_mul_f32_e32 v144, v168, v200
	v_mul_f32_e32 v145, v169, v201
	v_mul_f32_e32 v146, v170, v202
	v_mul_f32_e32 v147, v171, v203
	v_fmac_f32_e32 v140, v172, v188
	v_fmac_f32_e32 v141, v173, v189
	v_fmac_f32_e32 v142, v174, v190
	v_fmac_f32_e32 v143, v175, v191
	v_fmac_f32_e32 v144, v176, v192
	v_fmac_f32_e32 v145, v177, v193
	v_fmac_f32_e32 v146, v178, v194
	v_fmac_f32_e32 v147, v179, v195
	v_fmac_f32_e32 v140, v180, v204
	v_fmac_f32_e32 v141, v181, v205
	v_fmac_f32_e32 v142, v182, v206
	v_fmac_f32_e32 v143, v183, v207
	v_fmac_f32_e32 v144, v184, v208
	v_fmac_f32_e32 v145, v185, v209
	v_fmac_f32_e32 v146, v186, v210
	v_fmac_f32_e32 v147, v187, v211
	v_lshlrev_b32_e32 v150, 16, v34
	v_and_b32_e32 v151, 0xffff0000, v34
	v_mul_f32_e32 v140, v150, v140
	v_mul_f32_e32 v141, v151, v141
	v_lshlrev_b32_e32 v150, 16, v35
	v_and_b32_e32 v151, 0xffff0000, v35
	v_mul_f32_e32 v142, v150, v142
	v_mul_f32_e32 v143, v151, v143
	v_lshlrev_b32_e32 v150, 16, v36
	v_and_b32_e32 v151, 0xffff0000, v36
	v_mul_f32_e32 v144, v150, v144
	v_mul_f32_e32 v145, v151, v145
	v_lshlrev_b32_e32 v150, 16, v37
	v_and_b32_e32 v151, 0xffff0000, v37
	v_mul_f32_e32 v146, v150, v146
	v_mul_f32_e32 v147, v151, v147
	v_mul_f32_e32 v148, v140, v140
	v_fmac_f32_e32 v148, v141, v141
	v_fmac_f32_e32 v148, v142, v142
	v_fmac_f32_e32 v148, v143, v143
	v_fmac_f32_e32 v148, v144, v144
	v_fmac_f32_e32 v148, v145, v145
	v_fmac_f32_e32 v148, v146, v146
	v_fmac_f32_e32 v148, v147, v147
	v_mad_i64_i32 v[152:153], vcc, s41, v221, v[58:59]
	s_add_u32 s41, s41, 1
	global_load_dwordx4 v[34:37], v[152:153], off offset:1536 nt
	global_load_dwordx4 v[60:63], v[152:153], off offset:2560 nt
	s_nop 1
	v_add_f32_dpp v148, v148, v148 quad_perm:[1,0,3,2] row_mask:0xf bank_mask:0xf
	s_nop 1
	v_add_f32_dpp v148, v148, v148 quad_perm:[2,3,0,1] row_mask:0xf bank_mask:0xf
	s_nop 1
	v_add_f32_dpp v148, v148, v148 row_half_mirror row_mask:0xf bank_mask:0xf
	s_nop 1
	v_add_f32_dpp v148, v148, v148 row_mirror row_mask:0xf bank_mask:0xf
	s_nop 1
	v_add_f32_dpp v148, v148, v148 row_bcast:15 row_mask:0xa bank_mask:0xf
	s_nop 1
	v_add_f32_dpp v148, v148, v148 row_bcast:31 row_mask:0xc bank_mask:0xf
	s_nop 0
	v_readlane_b32 s0, v148, 63
	s_nop 1
	v_mov_b32_e32 v148, s0
	v_fmamk_f32 v148, v148, 0x3b000000, v162
	v_mul_f32_e32 v150, 0x4b800000, v148
	v_cmp_gt_f32_e32 vcc, s31, v148
	s_nop 1
	v_cndmask_b32_e32 v148, v148, v150, vcc
	v_rsq_f32_e32 v148, v148
	s_nop 0
	v_mul_f32_e32 v150, 0x45800000, v148
	v_cndmask_b32_e32 v149, v148, v150, vcc
	v_mul_f32_e32 v140, v149, v140
	v_mul_f32_e32 v141, v149, v141
	v_mul_f32_e32 v142, v149, v142
	v_mul_f32_e32 v143, v149, v143
	v_mul_f32_e32 v144, v149, v144
	v_mul_f32_e32 v145, v149, v145
	v_mul_f32_e32 v146, v149, v146
	v_mul_f32_e32 v147, v149, v147
	v_cvt_pk_bf16_f32 v140, v140, v141
	v_cvt_pk_bf16_f32 v141, v142, v143
	v_cvt_pk_bf16_f32 v142, v144, v145
	v_cvt_pk_bf16_f32 v143, v146, v147
	global_store_dwordx4 v[156:157], v[140:143], off sc1
	s_waitcnt vmcnt(15)
; __device__ __forceinline__ unsigned cvt_pk_bf16(float lo, float hi) { unsigned r; asm volatile("v_cvt_pk_bf16_f32 %0, %1, %2" : "=v"(r) : "v"(lo), "v"(hi)); return r; }
; __device__ __forceinline__ float bf_lo(unsigned w) { return __uint_as_float(w << 16); }
; __device__ __forceinline__ float bf_hi(unsigned w) { return __uint_as_float(w & 0xffff0000u); }
; __global__ void __launch_bounds__(512, 2) trunk_fwd(Args args) {
;     ...
;                 for (int rr = 0; rr < 16; ++rr) {
;                     const int r = r0 + rr;
;                     const u32x4 gb = gb_n, gu = gu_n; const f32x4 pv4 = pv_n;
;                     if (rr < 15) { gb_n = *(const u32x4*)(Z + (size_t)(r + 1) * INP + 768 + c0); gu_n = *(const u32x4*)(Z + (size_t)(r + 1) * INP + 1280 + c0);
;                                    pv_n = *(const f32x4*)(pl + (size_t)(r + 1) * PLE + lane * 4); }
;                     float cv[8], uu[8]; float ss = 0.f;
; #pragma unroll
;                     for (int i = 0; i < 4; ++i) {
;                         uu[2 * i] = bf_lo(gu[i]); uu[2 * i + 1] = bf_hi(gu[i]);
;                         cv[2 * i] = bf_lo(gb[i]) * (w0[2 * i] * uu[2 * i] + w1[2 * i] * u1[2 * i] + w2[2 * i] * u2[2 * i]);
;                         cv[2 * i + 1] = bf_hi(gb[i]) * (w0[2 * i + 1] * uu[2 * i + 1] + w1[2 * i + 1] * u1[2 * i + 1] + w2[2 * i + 1] * u2[2 * i + 1]);
;                     }
; #pragma unroll
;                     for (int i = 0; i < 8; ++i) { ss += cv[i] * cv[i]; u2[i] = u1[i]; u1[i] = uu[i]; }
;                     ss = wave_sum(ss);
;                     const float rc = rsqrtf(ss * (1.0f / 512.0f) + EPS);
;                     u32x4 oc;
; #pragma unroll
;                     for (int i = 0; i < 4; ++i) oc[i] = cvt_pk_bf16(cv[2 * i] * rc, cv[2 * i + 1] * rc);
;                     *(u32x4*)(MIX + (size_t)r * 1024 + 512 + c0) = oc;
	v_lshlrev_b32_e32 v204, 16, v64
	v_and_b32_e32 v205, 0xffff0000, v64
	v_lshlrev_b32_e32 v206, 16, v65
	v_and_b32_e32 v207, 0xffff0000, v65
	v_lshlrev_b32_e32 v208, 16, v66
	v_and_b32_e32 v209, 0xffff0000, v66
	v_lshlrev_b32_e32 v210, 16, v67
	v_and_b32_e32 v211, 0xffff0000, v67
	v_mul_f32_e32 v140, v164, v204
	v_mul_f32_e32 v141, v165, v205
	v_mul_f32_e32 v142, v166, v206
	v_mul_f32_e32 v143, v167, v207
	v_mul_f32_e32 v144, v168, v208
	v_mul_f32_e32 v145, v169, v209
	v_mul_f32_e32 v146, v170, v210
	v_mul_f32_e32 v147, v171, v211
	v_fmac_f32_e32 v140, v172, v196
	v_fmac_f32_e32 v141, v173, v197
	v_fmac_f32_e32 v142, v174, v198
	v_fmac_f32_e32 v143, v175, v199
	v_fmac_f32_e32 v144, v176, v200
	v_fmac_f32_e32 v145, v177, v201
	v_fmac_f32_e32 v146, v178, v202
	v_fmac_f32_e32 v147, v179, v203
	v_fmac_f32_e32 v140, v180, v188
	v_fmac_f32_e32 v141, v181, v189
	v_fmac_f32_e32 v142, v182, v190
	v_fmac_f32_e32 v143, v183, v191
	v_fmac_f32_e32 v144, v184, v192
	v_fmac_f32_e32 v145, v185, v193
	v_fmac_f32_e32 v146, v186, v194
	v_fmac_f32_e32 v147, v187, v195
	v_lshlrev_b32_e32 v150, 16, v38
	v_and_b32_e32 v151, 0xffff0000, v38
	v_mul_f32_e32 v140, v150, v140
	v_mul_f32_e32 v141, v151, v141
	v_lshlrev_b32_e32 v150, 16, v39
	v_and_b32_e32 v151, 0xffff0000, v39
	v_mul_f32_e32 v142, v150, v142
	v_mul_f32_e32 v143, v151, v143
	v_lshlrev_b32_e32 v150, 16, v40
	v_and_b32_e32 v151, 0xffff0000, v40
	v_mul_f32_e32 v144, v150, v144
	v_mul_f32_e32 v145, v151, v145
	v_lshlrev_b32_e32 v150, 16, v41
	v_and_b32_e32 v151, 0xffff0000, v41
	v_mul_f32_e32 v146, v150, v146
	v_mul_f32_e32 v147, v151, v147
	v_mul_f32_e32 v148, v140, v140
	v_fmac_f32_e32 v148, v141, v141
	v_fmac_f32_e32 v148, v142, v142
	v_fmac_f32_e32 v148, v143, v143
	v_fmac_f32_e32 v148, v144, v144
	v_fmac_f32_e32 v148, v145, v145
	v_fmac_f32_e32 v148, v146, v146
	v_fmac_f32_e32 v148, v147, v147
	v_mad_i64_i32 v[152:153], vcc, s41, v221, v[58:59]
	s_add_u32 s41, s41, 1
	global_load_dwordx4 v[38:41], v[152:153], off offset:1536 nt
	global_load_dwordx4 v[64:67], v[152:153], off offset:2560 nt
	s_nop 1
	v_add_f32_dpp v148, v148, v148 quad_perm:[1,0,3,2] row_mask:0xf bank_mask:0xf
	s_nop 1
	v_add_f32_dpp v148, v148, v148 quad_perm:[2,3,0,1] row_mask:0xf bank_mask:0xf
	s_nop 1
	v_add_f32_dpp v148, v148, v148 row_half_mirror row_mask:0xf bank_mask:0xf
	s_nop 1
	v_add_f32_dpp v148, v148, v148 row_mirror row_mask:0xf bank_mask:0xf
	s_nop 1
	v_add_f32_dpp v148, v148, v148 row_bcast:15 row_mask:0xa bank_mask:0xf
	s_nop 1
	v_add_f32_dpp v148, v148, v148 row_bcast:31 row_mask:0xc bank_mask:0xf
	s_nop 0
	v_readlane_b32 s0, v148, 63
	s_nop 1
	v_mov_b32_e32 v148, s0
	v_fmamk_f32 v148, v148, 0x3b000000, v162
	v_mul_f32_e32 v150, 0x4b800000, v148
	v_cmp_gt_f32_e32 vcc, s31, v148
	s_nop 1
	v_cndmask_b32_e32 v148, v148, v150, vcc
	v_rsq_f32_e32 v148, v148
	s_nop 0
	v_mul_f32_e32 v150, 0x45800000, v148
	v_cndmask_b32_e32 v149, v148, v150, vcc
	v_mul_f32_e32 v140, v149, v140
	v_mul_f32_e32 v141, v149, v141
	v_mul_f32_e32 v142, v149, v142
	v_mul_f32_e32 v143, v149, v143
	v_mul_f32_e32 v144, v149, v144
	v_mul_f32_e32 v145, v149, v145
	v_mul_f32_e32 v146, v149, v146
	v_mul_f32_e32 v147, v149, v147
	v_cvt_pk_bf16_f32 v140, v140, v141
	v_cvt_pk_bf16_f32 v141, v142, v143
	v_cvt_pk_bf16_f32 v142, v144, v145
	v_cvt_pk_bf16_f32 v143, v146, v147
	global_store_dwordx4 v[156:157], v[140:143], off offset:2048 sc1
	v_lshl_add_u64 v[156:157], v[156:157], 0, s[20:21]
	s_waitcnt vmcnt(16)
	v_lshlrev_b32_e32 v188, 16, v18
	v_and_b32_e32 v189, 0xffff0000, v18
	v_lshlrev_b32_e32 v190, 16, v19
	v_and_b32_e32 v191, 0xffff0000, v19
	v_lshlrev_b32_e32 v192, 16, v20
	v_and_b32_e32 v193, 0xffff0000, v20
	v_lshlrev_b32_e32 v194, 16, v21
	v_and_b32_e32 v195, 0xffff0000, v21
	v_mul_f32_e32 v140, v164, v188
	v_mul_f32_e32 v141, v165, v189
	v_mul_f32_e32 v142, v166, v190
	v_mul_f32_e32 v143, v167, v191
	v_mul_f32_e32 v144, v168, v192
	v_mul_f32_e32 v145, v169, v193
	v_mul_f32_e32 v146, v170, v194
	v_mul_f32_e32 v147, v171, v195
	v_fmac_f32_e32 v140, v172, v204
	v_fmac_f32_e32 v141, v173, v205
	v_fmac_f32_e32 v142, v174, v206
	v_fmac_f32_e32 v143, v175, v207
	v_fmac_f32_e32 v144, v176, v208
	v_fmac_f32_e32 v145, v177, v209
	v_fmac_f32_e32 v146, v178, v210
	v_fmac_f32_e32 v147, v179, v211
	v_fmac_f32_e32 v140, v180, v196
	v_fmac_f32_e32 v141, v181, v197
	v_fmac_f32_e32 v142, v182, v198
	v_fmac_f32_e32 v143, v183, v199
	v_fmac_f32_e32 v144, v184, v200
	v_fmac_f32_e32 v145, v185, v201
	v_fmac_f32_e32 v146, v186, v202
	v_fmac_f32_e32 v147, v187, v203
	v_lshlrev_b32_e32 v150, 16, v2
	v_and_b32_e32 v151, 0xffff0000, v2
	v_mul_f32_e32 v140, v150, v140
	v_mul_f32_e32 v141, v151, v141
	v_lshlrev_b32_e32 v150, 16, v3
	v_and_b32_e32 v151, 0xffff0000, v3
	v_mul_f32_e32 v142, v150, v142
	v_mul_f32_e32 v143, v151, v143
	v_lshlrev_b32_e32 v150, 16, v4
	v_and_b32_e32 v151, 0xffff0000, v4
	v_mul_f32_e32 v144, v150, v144
	v_mul_f32_e32 v145, v151, v145
	v_lshlrev_b32_e32 v150, 16, v5
	v_and_b32_e32 v151, 0xffff0000, v5
	v_mul_f32_e32 v146, v150, v146
	v_mul_f32_e32 v147, v151, v147
	v_mul_f32_e32 v148, v140, v140
	v_fmac_f32_e32 v148, v141, v141
	v_fmac_f32_e32 v148, v142, v142
	v_fmac_f32_e32 v148, v143, v143
	v_fmac_f32_e32 v148, v144, v144
	v_fmac_f32_e32 v148, v145, v145
	v_fmac_f32_e32 v148, v146, v146
	v_fmac_f32_e32 v148, v147, v147
	v_mad_i64_i32 v[152:153], vcc, s41, v221, v[58:59]
	s_add_u32 s41, s41, 1
	global_load_dwordx4 v[2:5], v[152:153], off offset:1536 nt
	global_load_dwordx4 v[18:21], v[152:153], off offset:2560 nt
	s_nop 1
	v_add_f32_dpp v148, v148, v148 quad_perm:[1,0,3,2] row_mask:0xf bank_mask:0xf
	s_nop 1
	v_add_f32_dpp v148, v148, v148 quad_perm:[2,3,0,1] row_mask:0xf bank_mask:0xf
	s_nop 1
	v_add_f32_dpp v148, v148, v148 row_half_mirror row_mask:0xf bank_mask:0xf
	s_nop 1
	v_add_f32_dpp v148, v148, v148 row_mirror row_mask:0xf bank_mask:0xf
	s_nop 1
	v_add_f32_dpp v148, v148, v148 row_bcast:15 row_mask:0xa bank_mask:0xf
	s_nop 1
	v_add_f32_dpp v148, v148, v148 row_bcast:31 row_mask:0xc bank_mask:0xf
	s_nop 0
	v_readlane_b32 s0, v148, 63
	s_nop 1
	v_mov_b32_e32 v148, s0
	v_fmamk_f32 v148, v148, 0x3b000000, v162
	v_mul_f32_e32 v150, 0x4b800000, v148
	v_cmp_gt_f32_e32 vcc, s31, v148
	s_nop 1
	v_cndmask_b32_e32 v148, v148, v150, vcc
	v_rsq_f32_e32 v148, v148
	s_nop 0
	v_mul_f32_e32 v150, 0x45800000, v148
	v_cndmask_b32_e32 v149, v148, v150, vcc
	v_mul_f32_e32 v140, v149, v140
	v_mul_f32_e32 v141, v149, v141
	v_mul_f32_e32 v142, v149, v142
	v_mul_f32_e32 v143, v149, v143
	v_mul_f32_e32 v144, v149, v144
	v_mul_f32_e32 v145, v149, v145
	v_mul_f32_e32 v146, v149, v146
	v_mul_f32_e32 v147, v149, v147
	v_cvt_pk_bf16_f32 v140, v140, v141
	v_cvt_pk_bf16_f32 v141, v142, v143
	v_cvt_pk_bf16_f32 v142, v144, v145
	v_cvt_pk_bf16_f32 v143, v146, v147
	global_store_dwordx4 v[156:157], v[140:143], off sc1
	s_waitcnt vmcnt(16)
; __device__ __forceinline__ unsigned cvt_pk_bf16(float lo, float hi) { unsigned r; asm volatile("v_cvt_pk_bf16_f32 %0, %1, %2" : "=v"(r) : "v"(lo), "v"(hi)); return r; }
; __device__ __forceinline__ float bf_lo(unsigned w) { return __uint_as_float(w << 16); }
; __device__ __forceinline__ float bf_hi(unsigned w) { return __uint_as_float(w & 0xffff0000u); }
; __global__ void __launch_bounds__(512, 2) trunk_fwd(Args args) {
;     ...
;                 for (int rr = 0; rr < 16; ++rr) {
;                     const int r = r0 + rr;
;                     const u32x4 gb = gb_n, gu = gu_n; const f32x4 pv4 = pv_n;
;                     if (rr < 15) { gb_n = *(const u32x4*)(Z + (size_t)(r + 1) * INP + 768 + c0); gu_n = *(const u32x4*)(Z + (size_t)(r + 1) * INP + 1280 + c0);
;                                    pv_n = *(const f32x4*)(pl + (size_t)(r + 1) * PLE + lane * 4); }
;                     float cv[8], uu[8]; float ss = 0.f;
; #pragma unroll
;                     for (int i = 0; i < 4; ++i) {
;                         uu[2 * i] = bf_lo(gu[i]); uu[2 * i + 1] = bf_hi(gu[i]);
;                         cv[2 * i] = bf_lo(gb[i]) * (w0[2 * i] * uu[2 * i] + w1[2 * i] * u1[2 * i] + w2[2 * i] * u2[2 * i]);
;                         cv[2 * i + 1] = bf_hi(gb[i]) * (w0[2 * i + 1] * uu[2 * i + 1] + w1[2 * i + 1] * u1[2 * i + 1] + w2[2 * i + 1] * u2[2 * i + 1]);
;                     }
; #pragma unroll
;                     for (int i = 0; i < 8; ++i) { ss += cv[i] * cv[i]; u2[i] = u1[i]; u1[i] = uu[i]; }
;                     ss = wave_sum(ss);
;                     const float rc = rsqrtf(ss * (1.0f / 512.0f) + EPS);
;                     u32x4 oc;
; #pragma unroll
;                     for (int i = 0; i < 4; ++i) oc[i] = cvt_pk_bf16(cv[2 * i] * rc, cv[2 * i + 1] * rc);
;                     *(u32x4*)(MIX + (size_t)r * 1024 + 512 + c0) = oc;
	v_lshlrev_b32_e32 v196, 16, v22
	v_and_b32_e32 v197, 0xffff0000, v22
	v_lshlrev_b32_e32 v198, 16, v23
	v_and_b32_e32 v199, 0xffff0000, v23
	v_lshlrev_b32_e32 v200, 16, v24
	v_and_b32_e32 v201, 0xffff0000, v24
	v_lshlrev_b32_e32 v202, 16, v25
	v_and_b32_e32 v203, 0xffff0000, v25
	v_mul_f32_e32 v140, v164, v196
	v_mul_f32_e32 v141, v165, v197
	v_mul_f32_e32 v142, v166, v198
	v_mul_f32_e32 v143, v167, v199
	v_mul_f32_e32 v144, v168, v200
	v_mul_f32_e32 v145, v169, v201
	v_mul_f32_e32 v146, v170, v202
	v_mul_f32_e32 v147, v171, v203
	v_fmac_f32_e32 v140, v172, v188
	v_fmac_f32_e32 v141, v173, v189
	v_fmac_f32_e32 v142, v174, v190
	v_fmac_f32_e32 v143, v175, v191
	v_fmac_f32_e32 v144, v176, v192
	v_fmac_f32_e32 v145, v177, v193
	v_fmac_f32_e32 v146, v178, v194
	v_fmac_f32_e32 v147, v179, v195
	v_fmac_f32_e32 v140, v180, v204
	v_fmac_f32_e32 v141, v181, v205
	v_fmac_f32_e32 v142, v182, v206
	v_fmac_f32_e32 v143, v183, v207
	v_fmac_f32_e32 v144, v184, v208
	v_fmac_f32_e32 v145, v185, v209
	v_fmac_f32_e32 v146, v186, v210
	v_fmac_f32_e32 v147, v187, v211
	v_lshlrev_b32_e32 v150, 16, v6
	v_and_b32_e32 v151, 0xffff0000, v6
	v_mul_f32_e32 v140, v150, v140
	v_mul_f32_e32 v141, v151, v141
	v_lshlrev_b32_e32 v150, 16, v7
	v_and_b32_e32 v151, 0xffff0000, v7
	v_mul_f32_e32 v142, v150, v142
	v_mul_f32_e32 v143, v151, v143
	v_lshlrev_b32_e32 v150, 16, v8
	v_and_b32_e32 v151, 0xffff0000, v8
	v_mul_f32_e32 v144, v150, v144
	v_mul_f32_e32 v145, v151, v145
	v_lshlrev_b32_e32 v150, 16, v9
	v_and_b32_e32 v151, 0xffff0000, v9
	v_mul_f32_e32 v146, v150, v146
	v_mul_f32_e32 v147, v151, v147
	v_mul_f32_e32 v148, v140, v140
	v_fmac_f32_e32 v148, v141, v141
	v_fmac_f32_e32 v148, v142, v142
	v_fmac_f32_e32 v148, v143, v143
	v_fmac_f32_e32 v148, v144, v144
	v_fmac_f32_e32 v148, v145, v145
	v_fmac_f32_e32 v148, v146, v146
	v_fmac_f32_e32 v148, v147, v147
	v_mad_i64_i32 v[152:153], vcc, s41, v221, v[58:59]
	s_add_u32 s41, s41, 1
	global_load_dwordx4 v[6:9], v[152:153], off offset:1536 nt
	global_load_dwordx4 v[22:25], v[152:153], off offset:2560 nt
	s_nop 1
	v_add_f32_dpp v148, v148, v148 quad_perm:[1,0,3,2] row_mask:0xf bank_mask:0xf
	s_nop 1
	v_add_f32_dpp v148, v148, v148 quad_perm:[2,3,0,1] row_mask:0xf bank_mask:0xf
	s_nop 1
	v_add_f32_dpp v148, v148, v148 row_half_mirror row_mask:0xf bank_mask:0xf
	s_nop 1
	v_add_f32_dpp v148, v148, v148 row_mirror row_mask:0xf bank_mask:0xf
	s_nop 1
	v_add_f32_dpp v148, v148, v148 row_bcast:15 row_mask:0xa bank_mask:0xf
	s_nop 1
	v_add_f32_dpp v148, v148, v148 row_bcast:31 row_mask:0xc bank_mask:0xf
	s_nop 0
	v_readlane_b32 s0, v148, 63
	s_nop 1
	v_mov_b32_e32 v148, s0
	v_fmamk_f32 v148, v148, 0x3b000000, v162
	v_mul_f32_e32 v150, 0x4b800000, v148
	v_cmp_gt_f32_e32 vcc, s31, v148
	s_nop 1
	v_cndmask_b32_e32 v148, v148, v150, vcc
	v_rsq_f32_e32 v148, v148
	s_nop 0
	v_mul_f32_e32 v150, 0x45800000, v148
	v_cndmask_b32_e32 v149, v148, v150, vcc
	v_mul_f32_e32 v140, v149, v140
	v_mul_f32_e32 v141, v149, v141
	v_mul_f32_e32 v142, v149, v142
	v_mul_f32_e32 v143, v149, v143
	v_mul_f32_e32 v144, v149, v144
	v_mul_f32_e32 v145, v149, v145
	v_mul_f32_e32 v146, v149, v146
	v_mul_f32_e32 v147, v149, v147
	v_cvt_pk_bf16_f32 v140, v140, v141
	v_cvt_pk_bf16_f32 v141, v142, v143
	v_cvt_pk_bf16_f32 v142, v144, v145
	v_cvt_pk_bf16_f32 v143, v146, v147
	global_store_dwordx4 v[156:157], v[140:143], off offset:2048 sc1
	v_lshl_add_u64 v[156:157], v[156:157], 0, s[20:21]
	s_waitcnt vmcnt(16)
	v_lshlrev_b32_e32 v204, 16, v26
	v_and_b32_e32 v205, 0xffff0000, v26
	v_lshlrev_b32_e32 v206, 16, v27
	v_and_b32_e32 v207, 0xffff0000, v27
	v_lshlrev_b32_e32 v208, 16, v28
	v_and_b32_e32 v209, 0xffff0000, v28
	v_lshlrev_b32_e32 v210, 16, v29
	v_and_b32_e32 v211, 0xffff0000, v29
	v_mul_f32_e32 v140, v164, v204
	v_mul_f32_e32 v141, v165, v205
	v_mul_f32_e32 v142, v166, v206
	v_mul_f32_e32 v143, v167, v207
	v_mul_f32_e32 v144, v168, v208
	v_mul_f32_e32 v145, v169, v209
	v_mul_f32_e32 v146, v170, v210
	v_mul_f32_e32 v147, v171, v211
	v_fmac_f32_e32 v140, v172, v196
	v_fmac_f32_e32 v141, v173, v197
	v_fmac_f32_e32 v142, v174, v198
	v_fmac_f32_e32 v143, v175, v199
	v_fmac_f32_e32 v144, v176, v200
	v_fmac_f32_e32 v145, v177, v201
	v_fmac_f32_e32 v146, v178, v202
	v_fmac_f32_e32 v147, v179, v203
	v_fmac_f32_e32 v140, v180, v188
	v_fmac_f32_e32 v141, v181, v189
	v_fmac_f32_e32 v142, v182, v190
	v_fmac_f32_e32 v143, v183, v191
	v_fmac_f32_e32 v144, v184, v192
	v_fmac_f32_e32 v145, v185, v193
	v_fmac_f32_e32 v146, v186, v194
	v_fmac_f32_e32 v147, v187, v195
	v_lshlrev_b32_e32 v150, 16, v10
	v_and_b32_e32 v151, 0xffff0000, v10
	v_mul_f32_e32 v140, v150, v140
	v_mul_f32_e32 v141, v151, v141
	v_lshlrev_b32_e32 v150, 16, v11
	v_and_b32_e32 v151, 0xffff0000, v11
	v_mul_f32_e32 v142, v150, v142
	v_mul_f32_e32 v143, v151, v143
	v_lshlrev_b32_e32 v150, 16, v12
	v_and_b32_e32 v151, 0xffff0000, v12
	v_mul_f32_e32 v144, v150, v144
	v_mul_f32_e32 v145, v151, v145
	v_lshlrev_b32_e32 v150, 16, v13
	v_and_b32_e32 v151, 0xffff0000, v13
	v_mul_f32_e32 v146, v150, v146
	v_mul_f32_e32 v147, v151, v147
	v_mul_f32_e32 v148, v140, v140
	v_fmac_f32_e32 v148, v141, v141
	v_fmac_f32_e32 v148, v142, v142
	v_fmac_f32_e32 v148, v143, v143
	v_fmac_f32_e32 v148, v144, v144
	v_fmac_f32_e32 v148, v145, v145
	v_fmac_f32_e32 v148, v146, v146
	v_fmac_f32_e32 v148, v147, v147
	v_mad_i64_i32 v[152:153], vcc, s41, v221, v[58:59]
	s_add_u32 s41, s41, 1
	global_load_dwordx4 v[10:13], v[152:153], off offset:1536 nt
	global_load_dwordx4 v[26:29], v[152:153], off offset:2560 nt
	s_nop 1
	v_add_f32_dpp v148, v148, v148 quad_perm:[1,0,3,2] row_mask:0xf bank_mask:0xf
	s_nop 1
	v_add_f32_dpp v148, v148, v148 quad_perm:[2,3,0,1] row_mask:0xf bank_mask:0xf
	s_nop 1
	v_add_f32_dpp v148, v148, v148 row_half_mirror row_mask:0xf bank_mask:0xf
	s_nop 1
	v_add_f32_dpp v148, v148, v148 row_mirror row_mask:0xf bank_mask:0xf
	s_nop 1
	v_add_f32_dpp v148, v148, v148 row_bcast:15 row_mask:0xa bank_mask:0xf
	s_nop 1
	v_add_f32_dpp v148, v148, v148 row_bcast:31 row_mask:0xc bank_mask:0xf
	s_nop 0
	v_readlane_b32 s0, v148, 63
	s_nop 1
	v_mov_b32_e32 v148, s0
	v_fmamk_f32 v148, v148, 0x3b000000, v162
	v_mul_f32_e32 v150, 0x4b800000, v148
	v_cmp_gt_f32_e32 vcc, s31, v148
	s_nop 1
	v_cndmask_b32_e32 v148, v148, v150, vcc
	v_rsq_f32_e32 v148, v148
	s_nop 0
	v_mul_f32_e32 v150, 0x45800000, v148
	v_cndmask_b32_e32 v149, v148, v150, vcc
	v_mul_f32_e32 v140, v149, v140
	v_mul_f32_e32 v141, v149, v141
	v_mul_f32_e32 v142, v149, v142
	v_mul_f32_e32 v143, v149, v143
	v_mul_f32_e32 v144, v149, v144
	v_mul_f32_e32 v145, v149, v145
	v_mul_f32_e32 v146, v149, v146
	v_mul_f32_e32 v147, v149, v147
	v_cvt_pk_bf16_f32 v140, v140, v141
	v_cvt_pk_bf16_f32 v141, v142, v143
	v_cvt_pk_bf16_f32 v142, v144, v145
	v_cvt_pk_bf16_f32 v143, v146, v147
	global_store_dwordx4 v[156:157], v[140:143], off sc1
	s_waitcnt vmcnt(16)
; __device__ __forceinline__ unsigned cvt_pk_bf16(float lo, float hi) { unsigned r; asm volatile("v_cvt_pk_bf16_f32 %0, %1, %2" : "=v"(r) : "v"(lo), "v"(hi)); return r; }
; __device__ __forceinline__ float bf_lo(unsigned w) { return __uint_as_float(w << 16); }
; __device__ __forceinline__ float bf_hi(unsigned w) { return __uint_as_float(w & 0xffff0000u); }
; __global__ void __launch_bounds__(512, 2) trunk_fwd(Args args) {
;     ...
;                 for (int rr = 0; rr < 16; ++rr) {
;                     const int r = r0 + rr;
;                     const u32x4 gb = gb_n, gu = gu_n; const f32x4 pv4 = pv_n;
;                     if (rr < 15) { gb_n = *(const u32x4*)(Z + (size_t)(r + 1) * INP + 768 + c0); gu_n = *(const u32x4*)(Z + (size_t)(r + 1) * INP + 1280 + c0);
;                                    pv_n = *(const f32x4*)(pl + (size_t)(r + 1) * PLE + lane * 4); }
;                     float cv[8], uu[8]; float ss = 0.f;
; #pragma unroll
;                     for (int i = 0; i < 4; ++i) {
;                         uu[2 * i] = bf_lo(gu[i]); uu[2 * i + 1] = bf_hi(gu[i]);
;                         cv[2 * i] = bf_lo(gb[i]) * (w0[2 * i] * uu[2 * i] + w1[2 * i] * u1[2 * i] + w2[2 * i] * u2[2 * i]);
;                         cv[2 * i + 1] = bf_hi(gb[i]) * (w0[2 * i + 1] * uu[2 * i + 1] + w1[2 * i + 1] * u1[2 * i + 1] + w2[2 * i + 1] * u2[2 * i + 1]);
;                     }
; #pragma unroll
;                     for (int i = 0; i < 8; ++i) { ss += cv[i] * cv[i]; u2[i] = u1[i]; u1[i] = uu[i]; }
;                     ss = wave_sum(ss);
;                     const float rc = rsqrtf(ss * (1.0f / 512.0f) + EPS);
;                     u32x4 oc;
; #pragma unroll
;                     for (int i = 0; i < 4; ++i) oc[i] = cvt_pk_bf16(cv[2 * i] * rc, cv[2 * i + 1] * rc);
;                     *(u32x4*)(MIX + (size_t)r * 1024 + 512 + c0) = oc;
	v_lshlrev_b32_e32 v188, 16, v30
	v_and_b32_e32 v189, 0xffff0000, v30
	v_lshlrev_b32_e32 v190, 16, v31
	v_and_b32_e32 v191, 0xffff0000, v31
	v_lshlrev_b32_e32 v192, 16, v32
	v_and_b32_e32 v193, 0xffff0000, v32
	v_lshlrev_b32_e32 v194, 16, v33
	v_and_b32_e32 v195, 0xffff0000, v33
	v_mul_f32_e32 v140, v164, v188
	v_mul_f32_e32 v141, v165, v189
	v_mul_f32_e32 v142, v166, v190
	v_mul_f32_e32 v143, v167, v191
	v_mul_f32_e32 v144, v168, v192
	v_mul_f32_e32 v145, v169, v193
	v_mul_f32_e32 v146, v170, v194
	v_mul_f32_e32 v147, v171, v195
	v_fmac_f32_e32 v140, v172, v204
	v_fmac_f32_e32 v141, v173, v205
	v_fmac_f32_e32 v142, v174, v206
	v_fmac_f32_e32 v143, v175, v207
	v_fmac_f32_e32 v144, v176, v208
	v_fmac_f32_e32 v145, v177, v209
	v_fmac_f32_e32 v146, v178, v210
	v_fmac_f32_e32 v147, v179, v211
	v_fmac_f32_e32 v140, v180, v196
	v_fmac_f32_e32 v141, v181, v197
	v_fmac_f32_e32 v142, v182, v198
	v_fmac_f32_e32 v143, v183, v199
	v_fmac_f32_e32 v144, v184, v200
	v_fmac_f32_e32 v145, v185, v201
	v_fmac_f32_e32 v146, v186, v202
	v_fmac_f32_e32 v147, v187, v203
	v_lshlrev_b32_e32 v150, 16, v14
	v_and_b32_e32 v151, 0xffff0000, v14
	v_mul_f32_e32 v140, v150, v140
	v_mul_f32_e32 v141, v151, v141
	v_lshlrev_b32_e32 v150, 16, v15
	v_and_b32_e32 v151, 0xffff0000, v15
	v_mul_f32_e32 v142, v150, v142
	v_mul_f32_e32 v143, v151, v143
	v_lshlrev_b32_e32 v150, 16, v16
	v_and_b32_e32 v151, 0xffff0000, v16
	v_mul_f32_e32 v144, v150, v144
	v_mul_f32_e32 v145, v151, v145
	v_lshlrev_b32_e32 v150, 16, v17
	v_and_b32_e32 v151, 0xffff0000, v17
	v_mul_f32_e32 v146, v150, v146
	v_mul_f32_e32 v147, v151, v147
	v_mul_f32_e32 v148, v140, v140
	v_fmac_f32_e32 v148, v141, v141
	v_fmac_f32_e32 v148, v142, v142
	v_fmac_f32_e32 v148, v143, v143
	v_fmac_f32_e32 v148, v144, v144
	v_fmac_f32_e32 v148, v145, v145
	v_fmac_f32_e32 v148, v146, v146
	v_fmac_f32_e32 v148, v147, v147
	v_mad_i64_i32 v[152:153], vcc, s41, v221, v[58:59]
	s_add_u32 s41, s41, 1
	global_load_dwordx4 v[14:17], v[152:153], off offset:1536 nt
	global_load_dwordx4 v[30:33], v[152:153], off offset:2560 nt
	s_nop 1
	v_add_f32_dpp v148, v148, v148 quad_perm:[1,0,3,2] row_mask:0xf bank_mask:0xf
	s_nop 1
	v_add_f32_dpp v148, v148, v148 quad_perm:[2,3,0,1] row_mask:0xf bank_mask:0xf
	s_nop 1
	v_add_f32_dpp v148, v148, v148 row_half_mirror row_mask:0xf bank_mask:0xf
	s_nop 1
	v_add_f32_dpp v148, v148, v148 row_mirror row_mask:0xf bank_mask:0xf
	s_nop 1
	v_add_f32_dpp v148, v148, v148 row_bcast:15 row_mask:0xa bank_mask:0xf
	s_nop 1
	v_add_f32_dpp v148, v148, v148 row_bcast:31 row_mask:0xc bank_mask:0xf
	s_nop 0
	v_readlane_b32 s0, v148, 63
	s_nop 1
	v_mov_b32_e32 v148, s0
	v_fmamk_f32 v148, v148, 0x3b000000, v162
	v_mul_f32_e32 v150, 0x4b800000, v148
	v_cmp_gt_f32_e32 vcc, s31, v148
	s_nop 1
	v_cndmask_b32_e32 v148, v148, v150, vcc
	v_rsq_f32_e32 v148, v148
	s_nop 0
	v_mul_f32_e32 v150, 0x45800000, v148
	v_cndmask_b32_e32 v149, v148, v150, vcc
	v_mul_f32_e32 v140, v149, v140
	v_mul_f32_e32 v141, v149, v141
	v_mul_f32_e32 v142, v149, v142
	v_mul_f32_e32 v143, v149, v143
	v_mul_f32_e32 v144, v149, v144
	v_mul_f32_e32 v145, v149, v145
	v_mul_f32_e32 v146, v149, v146
	v_mul_f32_e32 v147, v149, v147
	v_cvt_pk_bf16_f32 v140, v140, v141
	v_cvt_pk_bf16_f32 v141, v142, v143
	v_cvt_pk_bf16_f32 v142, v144, v145
	v_cvt_pk_bf16_f32 v143, v146, v147
	global_store_dwordx4 v[156:157], v[140:143], off offset:2048 sc1
	v_lshl_add_u64 v[156:157], v[156:157], 0, s[20:21]
	s_waitcnt vmcnt(16)
	v_lshlrev_b32_e32 v196, 16, v60
	v_and_b32_e32 v197, 0xffff0000, v60
	v_lshlrev_b32_e32 v198, 16, v61
	v_and_b32_e32 v199, 0xffff0000, v61
	v_lshlrev_b32_e32 v200, 16, v62
	v_and_b32_e32 v201, 0xffff0000, v62
	v_lshlrev_b32_e32 v202, 16, v63
	v_and_b32_e32 v203, 0xffff0000, v63
	v_mul_f32_e32 v140, v164, v196
	v_mul_f32_e32 v141, v165, v197
	v_mul_f32_e32 v142, v166, v198
	v_mul_f32_e32 v143, v167, v199
	v_mul_f32_e32 v144, v168, v200
	v_mul_f32_e32 v145, v169, v201
	v_mul_f32_e32 v146, v170, v202
	v_mul_f32_e32 v147, v171, v203
	v_fmac_f32_e32 v140, v172, v188
	v_fmac_f32_e32 v141, v173, v189
	v_fmac_f32_e32 v142, v174, v190
	v_fmac_f32_e32 v143, v175, v191
	v_fmac_f32_e32 v144, v176, v192
	v_fmac_f32_e32 v145, v177, v193
	v_fmac_f32_e32 v146, v178, v194
	v_fmac_f32_e32 v147, v179, v195
	v_fmac_f32_e32 v140, v180, v204
	v_fmac_f32_e32 v141, v181, v205
	v_fmac_f32_e32 v142, v182, v206
	v_fmac_f32_e32 v143, v183, v207
	v_fmac_f32_e32 v144, v184, v208
	v_fmac_f32_e32 v145, v185, v209
	v_fmac_f32_e32 v146, v186, v210
	v_fmac_f32_e32 v147, v187, v211
	v_lshlrev_b32_e32 v150, 16, v34
	v_and_b32_e32 v151, 0xffff0000, v34
	v_mul_f32_e32 v140, v150, v140
	v_mul_f32_e32 v141, v151, v141
	v_lshlrev_b32_e32 v150, 16, v35
	v_and_b32_e32 v151, 0xffff0000, v35
	v_mul_f32_e32 v142, v150, v142
	v_mul_f32_e32 v143, v151, v143
	v_lshlrev_b32_e32 v150, 16, v36
	v_and_b32_e32 v151, 0xffff0000, v36
	v_mul_f32_e32 v144, v150, v144
	v_mul_f32_e32 v145, v151, v145
	v_lshlrev_b32_e32 v150, 16, v37
	v_and_b32_e32 v151, 0xffff0000, v37
	v_mul_f32_e32 v146, v150, v146
	v_mul_f32_e32 v147, v151, v147
	v_mul_f32_e32 v148, v140, v140
	v_fmac_f32_e32 v148, v141, v141
	v_fmac_f32_e32 v148, v142, v142
	v_fmac_f32_e32 v148, v143, v143
	v_fmac_f32_e32 v148, v144, v144
	v_fmac_f32_e32 v148, v145, v145
	v_fmac_f32_e32 v148, v146, v146
	v_fmac_f32_e32 v148, v147, v147
	s_nop 1
	v_add_f32_dpp v148, v148, v148 quad_perm:[1,0,3,2] row_mask:0xf bank_mask:0xf
	s_nop 1
	v_add_f32_dpp v148, v148, v148 quad_perm:[2,3,0,1] row_mask:0xf bank_mask:0xf
	s_nop 1
	v_add_f32_dpp v148, v148, v148 row_half_mirror row_mask:0xf bank_mask:0xf
	s_nop 1
	v_add_f32_dpp v148, v148, v148 row_mirror row_mask:0xf bank_mask:0xf
	s_nop 1
	v_add_f32_dpp v148, v148, v148 row_bcast:15 row_mask:0xa bank_mask:0xf
	s_nop 1
	v_add_f32_dpp v148, v148, v148 row_bcast:31 row_mask:0xc bank_mask:0xf
	s_nop 0
	v_readlane_b32 s0, v148, 63
	s_nop 1
	v_mov_b32_e32 v148, s0
	v_fmamk_f32 v148, v148, 0x3b000000, v162
	v_mul_f32_e32 v150, 0x4b800000, v148
	v_cmp_gt_f32_e32 vcc, s31, v148
	s_nop 1
	v_cndmask_b32_e32 v148, v148, v150, vcc
	v_rsq_f32_e32 v148, v148
	s_nop 0
	v_mul_f32_e32 v150, 0x45800000, v148
	v_cndmask_b32_e32 v149, v148, v150, vcc
	v_mul_f32_e32 v140, v149, v140
	v_mul_f32_e32 v141, v149, v141
	v_mul_f32_e32 v142, v149, v142
	v_mul_f32_e32 v143, v149, v143
	v_mul_f32_e32 v144, v149, v144
	v_mul_f32_e32 v145, v149, v145
	v_mul_f32_e32 v146, v149, v146
	v_mul_f32_e32 v147, v149, v147
	v_cvt_pk_bf16_f32 v140, v140, v141
	v_cvt_pk_bf16_f32 v141, v142, v143
	v_cvt_pk_bf16_f32 v142, v144, v145
	v_cvt_pk_bf16_f32 v143, v146, v147
	global_store_dwordx4 v[156:157], v[140:143], off sc1
	s_waitcnt vmcnt(14)
; __device__ __forceinline__ unsigned cvt_pk_bf16(float lo, float hi) { unsigned r; asm volatile("v_cvt_pk_bf16_f32 %0, %1, %2" : "=v"(r) : "v"(lo), "v"(hi)); return r; }
; __device__ __forceinline__ float bf_lo(unsigned w) { return __uint_as_float(w << 16); }
; __device__ __forceinline__ float bf_hi(unsigned w) { return __uint_as_float(w & 0xffff0000u); }
; __global__ void __launch_bounds__(512, 2) trunk_fwd(Args args) {
;     ...
;                 for (int rr = 0; rr < 16; ++rr) {
;                     const int r = r0 + rr;
;                     const u32x4 gb = gb_n, gu = gu_n; const f32x4 pv4 = pv_n;
;                     if (rr < 15) { gb_n = *(const u32x4*)(Z + (size_t)(r + 1) * INP + 768 + c0); gu_n = *(const u32x4*)(Z + (size_t)(r + 1) * INP + 1280 + c0);
;                                    pv_n = *(const f32x4*)(pl + (size_t)(r + 1) * PLE + lane * 4); }
;                     float cv[8], uu[8]; float ss = 0.f;
; #pragma unroll
;                     for (int i = 0; i < 4; ++i) {
;                         uu[2 * i] = bf_lo(gu[i]); uu[2 * i + 1] = bf_hi(gu[i]);
;                         cv[2 * i] = bf_lo(gb[i]) * (w0[2 * i] * uu[2 * i] + w1[2 * i] * u1[2 * i] + w2[2 * i] * u2[2 * i]);
;                         cv[2 * i + 1] = bf_hi(gb[i]) * (w0[2 * i + 1] * uu[2 * i + 1] + w1[2 * i + 1] * u1[2 * i + 1] + w2[2 * i + 1] * u2[2 * i + 1]);
;                     }
; #pragma unroll
;                     for (int i = 0; i < 8; ++i) { ss += cv[i] * cv[i]; u2[i] = u1[i]; u1[i] = uu[i]; }
;                     ss = wave_sum(ss);
;                     const float rc = rsqrtf(ss * (1.0f / 512.0f) + EPS);
;                     u32x4 oc;
; #pragma unroll
;                     for (int i = 0; i < 4; ++i) oc[i] = cvt_pk_bf16(cv[2 * i] * rc, cv[2 * i + 1] * rc);
;                     *(u32x4*)(MIX + (size_t)r * 1024 + 512 + c0) = oc;
	v_lshlrev_b32_e32 v204, 16, v64
	v_and_b32_e32 v205, 0xffff0000, v64
	v_lshlrev_b32_e32 v206, 16, v65
	v_and_b32_e32 v207, 0xffff0000, v65
	v_lshlrev_b32_e32 v208, 16, v66
	v_and_b32_e32 v209, 0xffff0000, v66
	v_lshlrev_b32_e32 v210, 16, v67
	v_and_b32_e32 v211, 0xffff0000, v67
	v_mul_f32_e32 v140, v164, v204
	v_mul_f32_e32 v141, v165, v205
	v_mul_f32_e32 v142, v166, v206
	v_mul_f32_e32 v143, v167, v207
	v_mul_f32_e32 v144, v168, v208
	v_mul_f32_e32 v145, v169, v209
	v_mul_f32_e32 v146, v170, v210
	v_mul_f32_e32 v147, v171, v211
	v_fmac_f32_e32 v140, v172, v196
	v_fmac_f32_e32 v141, v173, v197
	v_fmac_f32_e32 v142, v174, v198
	v_fmac_f32_e32 v143, v175, v199
	v_fmac_f32_e32 v144, v176, v200
	v_fmac_f32_e32 v145, v177, v201
	v_fmac_f32_e32 v146, v178, v202
	v_fmac_f32_e32 v147, v179, v203
	v_fmac_f32_e32 v140, v180, v188
	v_fmac_f32_e32 v141, v181, v189
	v_fmac_f32_e32 v142, v182, v190
	v_fmac_f32_e32 v143, v183, v191
	v_fmac_f32_e32 v144, v184, v192
	v_fmac_f32_e32 v145, v185, v193
	v_fmac_f32_e32 v146, v186, v194
	v_fmac_f32_e32 v147, v187, v195
	v_lshlrev_b32_e32 v150, 16, v38
	v_and_b32_e32 v151, 0xffff0000, v38
	v_mul_f32_e32 v140, v150, v140
	v_mul_f32_e32 v141, v151, v141
	v_lshlrev_b32_e32 v150, 16, v39
	v_and_b32_e32 v151, 0xffff0000, v39
	v_mul_f32_e32 v142, v150, v142
	v_mul_f32_e32 v143, v151, v143
	v_lshlrev_b32_e32 v150, 16, v40
	v_and_b32_e32 v151, 0xffff0000, v40
	v_mul_f32_e32 v144, v150, v144
	v_mul_f32_e32 v145, v151, v145
	v_lshlrev_b32_e32 v150, 16, v41
	v_and_b32_e32 v151, 0xffff0000, v41
	v_mul_f32_e32 v146, v150, v146
	v_mul_f32_e32 v147, v151, v147
	v_mul_f32_e32 v148, v140, v140
	v_fmac_f32_e32 v148, v141, v141
	v_fmac_f32_e32 v148, v142, v142
	v_fmac_f32_e32 v148, v143, v143
	v_fmac_f32_e32 v148, v144, v144
	v_fmac_f32_e32 v148, v145, v145
	v_fmac_f32_e32 v148, v146, v146
	v_fmac_f32_e32 v148, v147, v147
	s_nop 1
	v_add_f32_dpp v148, v148, v148 quad_perm:[1,0,3,2] row_mask:0xf bank_mask:0xf
	s_nop 1
	v_add_f32_dpp v148, v148, v148 quad_perm:[2,3,0,1] row_mask:0xf bank_mask:0xf
	s_nop 1
	v_add_f32_dpp v148, v148, v148 row_half_mirror row_mask:0xf bank_mask:0xf
	s_nop 1
	v_add_f32_dpp v148, v148, v148 row_mirror row_mask:0xf bank_mask:0xf
	s_nop 1
	v_add_f32_dpp v148, v148, v148 row_bcast:15 row_mask:0xa bank_mask:0xf
	s_nop 1
	v_add_f32_dpp v148, v148, v148 row_bcast:31 row_mask:0xc bank_mask:0xf
	s_nop 0
	v_readlane_b32 s0, v148, 63
	s_nop 1
	v_mov_b32_e32 v148, s0
	v_fmamk_f32 v148, v148, 0x3b000000, v162
	v_mul_f32_e32 v150, 0x4b800000, v148
	v_cmp_gt_f32_e32 vcc, s31, v148
	s_nop 1
	v_cndmask_b32_e32 v148, v148, v150, vcc
	v_rsq_f32_e32 v148, v148
	s_nop 0
	v_mul_f32_e32 v150, 0x45800000, v148
	v_cndmask_b32_e32 v149, v148, v150, vcc
	v_mul_f32_e32 v140, v149, v140
	v_mul_f32_e32 v141, v149, v141
	v_mul_f32_e32 v142, v149, v142
	v_mul_f32_e32 v143, v149, v143
	v_mul_f32_e32 v144, v149, v144
	v_mul_f32_e32 v145, v149, v145
	v_mul_f32_e32 v146, v149, v146
	v_mul_f32_e32 v147, v149, v147
	v_cvt_pk_bf16_f32 v140, v140, v141
	v_cvt_pk_bf16_f32 v141, v142, v143
	v_cvt_pk_bf16_f32 v142, v144, v145
	v_cvt_pk_bf16_f32 v143, v146, v147
	global_store_dwordx4 v[156:157], v[140:143], off offset:2048 sc1
	v_lshl_add_u64 v[156:157], v[156:157], 0, s[20:21]
	s_waitcnt vmcnt(12)
	v_lshlrev_b32_e32 v188, 16, v18
	v_and_b32_e32 v189, 0xffff0000, v18
	v_lshlrev_b32_e32 v190, 16, v19
	v_and_b32_e32 v191, 0xffff0000, v19
	v_lshlrev_b32_e32 v192, 16, v20
	v_and_b32_e32 v193, 0xffff0000, v20
	v_lshlrev_b32_e32 v194, 16, v21
	v_and_b32_e32 v195, 0xffff0000, v21
	v_mul_f32_e32 v140, v164, v188
	v_mul_f32_e32 v141, v165, v189
	v_mul_f32_e32 v142, v166, v190
	v_mul_f32_e32 v143, v167, v191
	v_mul_f32_e32 v144, v168, v192
	v_mul_f32_e32 v145, v169, v193
	v_mul_f32_e32 v146, v170, v194
	v_mul_f32_e32 v147, v171, v195
	v_fmac_f32_e32 v140, v172, v204
	v_fmac_f32_e32 v141, v173, v205
	v_fmac_f32_e32 v142, v174, v206
	v_fmac_f32_e32 v143, v175, v207
	v_fmac_f32_e32 v144, v176, v208
	v_fmac_f32_e32 v145, v177, v209
	v_fmac_f32_e32 v146, v178, v210
	v_fmac_f32_e32 v147, v179, v211
	v_fmac_f32_e32 v140, v180, v196
	v_fmac_f32_e32 v141, v181, v197
	v_fmac_f32_e32 v142, v182, v198
	v_fmac_f32_e32 v143, v183, v199
	v_fmac_f32_e32 v144, v184, v200
	v_fmac_f32_e32 v145, v185, v201
	v_fmac_f32_e32 v146, v186, v202
	v_fmac_f32_e32 v147, v187, v203
	v_lshlrev_b32_e32 v150, 16, v2
	v_and_b32_e32 v151, 0xffff0000, v2
	v_mul_f32_e32 v140, v150, v140
	v_mul_f32_e32 v141, v151, v141
	v_lshlrev_b32_e32 v150, 16, v3
	v_and_b32_e32 v151, 0xffff0000, v3
	v_mul_f32_e32 v142, v150, v142
	v_mul_f32_e32 v143, v151, v143
	v_lshlrev_b32_e32 v150, 16, v4
	v_and_b32_e32 v151, 0xffff0000, v4
	v_mul_f32_e32 v144, v150, v144
	v_mul_f32_e32 v145, v151, v145
	v_lshlrev_b32_e32 v150, 16, v5
	v_and_b32_e32 v151, 0xffff0000, v5
	v_mul_f32_e32 v146, v150, v146
	v_mul_f32_e32 v147, v151, v147
	v_mul_f32_e32 v148, v140, v140
	v_fmac_f32_e32 v148, v141, v141
	v_fmac_f32_e32 v148, v142, v142
	v_fmac_f32_e32 v148, v143, v143
	v_fmac_f32_e32 v148, v144, v144
	v_fmac_f32_e32 v148, v145, v145
	v_fmac_f32_e32 v148, v146, v146
	v_fmac_f32_e32 v148, v147, v147
	s_nop 1
	v_add_f32_dpp v148, v148, v148 quad_perm:[1,0,3,2] row_mask:0xf bank_mask:0xf
	s_nop 1
	v_add_f32_dpp v148, v148, v148 quad_perm:[2,3,0,1] row_mask:0xf bank_mask:0xf
	s_nop 1
	v_add_f32_dpp v148, v148, v148 row_half_mirror row_mask:0xf bank_mask:0xf
	s_nop 1
	v_add_f32_dpp v148, v148, v148 row_mirror row_mask:0xf bank_mask:0xf
	s_nop 1
	v_add_f32_dpp v148, v148, v148 row_bcast:15 row_mask:0xa bank_mask:0xf
	s_nop 1
	v_add_f32_dpp v148, v148, v148 row_bcast:31 row_mask:0xc bank_mask:0xf
	s_nop 0
	v_readlane_b32 s0, v148, 63
	s_nop 1
	v_mov_b32_e32 v148, s0
	v_fmamk_f32 v148, v148, 0x3b000000, v162
	v_mul_f32_e32 v150, 0x4b800000, v148
	v_cmp_gt_f32_e32 vcc, s31, v148
	s_nop 1
	v_cndmask_b32_e32 v148, v148, v150, vcc
	v_rsq_f32_e32 v148, v148
	s_nop 0
	v_mul_f32_e32 v150, 0x45800000, v148
	v_cndmask_b32_e32 v149, v148, v150, vcc
	v_mul_f32_e32 v140, v149, v140
	v_mul_f32_e32 v141, v149, v141
	v_mul_f32_e32 v142, v149, v142
	v_mul_f32_e32 v143, v149, v143
	v_mul_f32_e32 v144, v149, v144
	v_mul_f32_e32 v145, v149, v145
	v_mul_f32_e32 v146, v149, v146
	v_mul_f32_e32 v147, v149, v147
	v_cvt_pk_bf16_f32 v140, v140, v141
	v_cvt_pk_bf16_f32 v141, v142, v143
	v_cvt_pk_bf16_f32 v142, v144, v145
	v_cvt_pk_bf16_f32 v143, v146, v147
	global_store_dwordx4 v[156:157], v[140:143], off sc1
	s_waitcnt vmcnt(10)
; __device__ __forceinline__ unsigned cvt_pk_bf16(float lo, float hi) { unsigned r; asm volatile("v_cvt_pk_bf16_f32 %0, %1, %2" : "=v"(r) : "v"(lo), "v"(hi)); return r; }
; __device__ __forceinline__ float bf_lo(unsigned w) { return __uint_as_float(w << 16); }
; __device__ __forceinline__ float bf_hi(unsigned w) { return __uint_as_float(w & 0xffff0000u); }
; __global__ void __launch_bounds__(512, 2) trunk_fwd(Args args) {
;     ...
;                 for (int rr = 0; rr < 16; ++rr) {
;                     const int r = r0 + rr;
;                     const u32x4 gb = gb_n, gu = gu_n; const f32x4 pv4 = pv_n;
;                     if (rr < 15) { gb_n = *(const u32x4*)(Z + (size_t)(r + 1) * INP + 768 + c0); gu_n = *(const u32x4*)(Z + (size_t)(r + 1) * INP + 1280 + c0);
;                                    pv_n = *(const f32x4*)(pl + (size_t)(r + 1) * PLE + lane * 4); }
;                     float cv[8], uu[8]; float ss = 0.f;
; #pragma unroll
;                     for (int i = 0; i < 4; ++i) {
;                         uu[2 * i] = bf_lo(gu[i]); uu[2 * i + 1] = bf_hi(gu[i]);
;                         cv[2 * i] = bf_lo(gb[i]) * (w0[2 * i] * uu[2 * i] + w1[2 * i] * u1[2 * i] + w2[2 * i] * u2[2 * i]);
;                         cv[2 * i + 1] = bf_hi(gb[i]) * (w0[2 * i + 1] * uu[2 * i + 1] + w1[2 * i + 1] * u1[2 * i + 1] + w2[2 * i + 1] * u2[2 * i + 1]);
;                     }
; #pragma unroll
;                     for (int i = 0; i < 8; ++i) { ss += cv[i] * cv[i]; u2[i] = u1[i]; u1[i] = uu[i]; }
;                     ss = wave_sum(ss);
;                     const float rc = rsqrtf(ss * (1.0f / 512.0f) + EPS);
;                     u32x4 oc;
; #pragma unroll
;                     for (int i = 0; i < 4; ++i) oc[i] = cvt_pk_bf16(cv[2 * i] * rc, cv[2 * i + 1] * rc);
;                     *(u32x4*)(MIX + (size_t)r * 1024 + 512 + c0) = oc;
	v_lshlrev_b32_e32 v196, 16, v22
	v_and_b32_e32 v197, 0xffff0000, v22
	v_lshlrev_b32_e32 v198, 16, v23
	v_and_b32_e32 v199, 0xffff0000, v23
	v_lshlrev_b32_e32 v200, 16, v24
	v_and_b32_e32 v201, 0xffff0000, v24
	v_lshlrev_b32_e32 v202, 16, v25
	v_and_b32_e32 v203, 0xffff0000, v25
	v_mul_f32_e32 v140, v164, v196
	v_mul_f32_e32 v141, v165, v197
	v_mul_f32_e32 v142, v166, v198
	v_mul_f32_e32 v143, v167, v199
	v_mul_f32_e32 v144, v168, v200
	v_mul_f32_e32 v145, v169, v201
	v_mul_f32_e32 v146, v170, v202
	v_mul_f32_e32 v147, v171, v203
	v_fmac_f32_e32 v140, v172, v188
	v_fmac_f32_e32 v141, v173, v189
	v_fmac_f32_e32 v142, v174, v190
	v_fmac_f32_e32 v143, v175, v191
	v_fmac_f32_e32 v144, v176, v192
	v_fmac_f32_e32 v145, v177, v193
	v_fmac_f32_e32 v146, v178, v194
	v_fmac_f32_e32 v147, v179, v195
	v_fmac_f32_e32 v140, v180, v204
	v_fmac_f32_e32 v141, v181, v205
	v_fmac_f32_e32 v142, v182, v206
	v_fmac_f32_e32 v143, v183, v207
	v_fmac_f32_e32 v144, v184, v208
	v_fmac_f32_e32 v145, v185, v209
	v_fmac_f32_e32 v146, v186, v210
	v_fmac_f32_e32 v147, v187, v211
	v_lshlrev_b32_e32 v150, 16, v6
	v_and_b32_e32 v151, 0xffff0000, v6
	v_mul_f32_e32 v140, v150, v140
	v_mul_f32_e32 v141, v151, v141
	v_lshlrev_b32_e32 v150, 16, v7
	v_and_b32_e32 v151, 0xffff0000, v7
	v_mul_f32_e32 v142, v150, v142
	v_mul_f32_e32 v143, v151, v143
	v_lshlrev_b32_e32 v150, 16, v8
	v_and_b32_e32 v151, 0xffff0000, v8
	v_mul_f32_e32 v144, v150, v144
	v_mul_f32_e32 v145, v151, v145
	v_lshlrev_b32_e32 v150, 16, v9
	v_and_b32_e32 v151, 0xffff0000, v9
	v_mul_f32_e32 v146, v150, v146
	v_mul_f32_e32 v147, v151, v147
	v_mul_f32_e32 v148, v140, v140
	v_fmac_f32_e32 v148, v141, v141
	v_fmac_f32_e32 v148, v142, v142
	v_fmac_f32_e32 v148, v143, v143
	v_fmac_f32_e32 v148, v144, v144
	v_fmac_f32_e32 v148, v145, v145
	v_fmac_f32_e32 v148, v146, v146
	v_fmac_f32_e32 v148, v147, v147
	s_nop 1
	v_add_f32_dpp v148, v148, v148 quad_perm:[1,0,3,2] row_mask:0xf bank_mask:0xf
	s_nop 1
	v_add_f32_dpp v148, v148, v148 quad_perm:[2,3,0,1] row_mask:0xf bank_mask:0xf
	s_nop 1
	v_add_f32_dpp v148, v148, v148 row_half_mirror row_mask:0xf bank_mask:0xf
	s_nop 1
	v_add_f32_dpp v148, v148, v148 row_mirror row_mask:0xf bank_mask:0xf
	s_nop 1
	v_add_f32_dpp v148, v148, v148 row_bcast:15 row_mask:0xa bank_mask:0xf
	s_nop 1
	v_add_f32_dpp v148, v148, v148 row_bcast:31 row_mask:0xc bank_mask:0xf
	s_nop 0
	v_readlane_b32 s0, v148, 63
	s_nop 1
	v_mov_b32_e32 v148, s0
	v_fmamk_f32 v148, v148, 0x3b000000, v162
	v_mul_f32_e32 v150, 0x4b800000, v148
	v_cmp_gt_f32_e32 vcc, s31, v148
	s_nop 1
	v_cndmask_b32_e32 v148, v148, v150, vcc
	v_rsq_f32_e32 v148, v148
	s_nop 0
	v_mul_f32_e32 v150, 0x45800000, v148
	v_cndmask_b32_e32 v149, v148, v150, vcc
	v_mul_f32_e32 v140, v149, v140
	v_mul_f32_e32 v141, v149, v141
	v_mul_f32_e32 v142, v149, v142
	v_mul_f32_e32 v143, v149, v143
	v_mul_f32_e32 v144, v149, v144
	v_mul_f32_e32 v145, v149, v145
	v_mul_f32_e32 v146, v149, v146
	v_mul_f32_e32 v147, v149, v147
	v_cvt_pk_bf16_f32 v140, v140, v141
	v_cvt_pk_bf16_f32 v141, v142, v143
	v_cvt_pk_bf16_f32 v142, v144, v145
	v_cvt_pk_bf16_f32 v143, v146, v147
	global_store_dwordx4 v[156:157], v[140:143], off offset:2048 sc1
	v_lshl_add_u64 v[156:157], v[156:157], 0, s[20:21]
	s_waitcnt vmcnt(8)
	v_lshlrev_b32_e32 v204, 16, v26
	v_and_b32_e32 v205, 0xffff0000, v26
	v_lshlrev_b32_e32 v206, 16, v27
	v_and_b32_e32 v207, 0xffff0000, v27
	v_lshlrev_b32_e32 v208, 16, v28
	v_and_b32_e32 v209, 0xffff0000, v28
	v_lshlrev_b32_e32 v210, 16, v29
	v_and_b32_e32 v211, 0xffff0000, v29
	v_mul_f32_e32 v140, v164, v204
	v_mul_f32_e32 v141, v165, v205
	v_mul_f32_e32 v142, v166, v206
	v_mul_f32_e32 v143, v167, v207
	v_mul_f32_e32 v144, v168, v208
	v_mul_f32_e32 v145, v169, v209
	v_mul_f32_e32 v146, v170, v210
	v_mul_f32_e32 v147, v171, v211
	v_fmac_f32_e32 v140, v172, v196
	v_fmac_f32_e32 v141, v173, v197
	v_fmac_f32_e32 v142, v174, v198
	v_fmac_f32_e32 v143, v175, v199
	v_fmac_f32_e32 v144, v176, v200
	v_fmac_f32_e32 v145, v177, v201
	v_fmac_f32_e32 v146, v178, v202
	v_fmac_f32_e32 v147, v179, v203
	v_fmac_f32_e32 v140, v180, v188
	v_fmac_f32_e32 v141, v181, v189
	v_fmac_f32_e32 v142, v182, v190
	v_fmac_f32_e32 v143, v183, v191
	v_fmac_f32_e32 v144, v184, v192
	v_fmac_f32_e32 v145, v185, v193
	v_fmac_f32_e32 v146, v186, v194
	v_fmac_f32_e32 v147, v187, v195
	v_lshlrev_b32_e32 v150, 16, v10
	v_and_b32_e32 v151, 0xffff0000, v10
	v_mul_f32_e32 v140, v150, v140
	v_mul_f32_e32 v141, v151, v141
	v_lshlrev_b32_e32 v150, 16, v11
	v_and_b32_e32 v151, 0xffff0000, v11
	v_mul_f32_e32 v142, v150, v142
	v_mul_f32_e32 v143, v151, v143
	v_lshlrev_b32_e32 v150, 16, v12
	v_and_b32_e32 v151, 0xffff0000, v12
	v_mul_f32_e32 v144, v150, v144
	v_mul_f32_e32 v145, v151, v145
	v_lshlrev_b32_e32 v150, 16, v13
	v_and_b32_e32 v151, 0xffff0000, v13
	v_mul_f32_e32 v146, v150, v146
	v_mul_f32_e32 v147, v151, v147
	v_mul_f32_e32 v148, v140, v140
	v_fmac_f32_e32 v148, v141, v141
	v_fmac_f32_e32 v148, v142, v142
	v_fmac_f32_e32 v148, v143, v143
	v_fmac_f32_e32 v148, v144, v144
	v_fmac_f32_e32 v148, v145, v145
	v_fmac_f32_e32 v148, v146, v146
	v_fmac_f32_e32 v148, v147, v147
	s_nop 1
	v_add_f32_dpp v148, v148, v148 quad_perm:[1,0,3,2] row_mask:0xf bank_mask:0xf
	s_nop 1
	v_add_f32_dpp v148, v148, v148 quad_perm:[2,3,0,1] row_mask:0xf bank_mask:0xf
	s_nop 1
	v_add_f32_dpp v148, v148, v148 row_half_mirror row_mask:0xf bank_mask:0xf
	s_nop 1
	v_add_f32_dpp v148, v148, v148 row_mirror row_mask:0xf bank_mask:0xf
	s_nop 1
	v_add_f32_dpp v148, v148, v148 row_bcast:15 row_mask:0xa bank_mask:0xf
	s_nop 1
	v_add_f32_dpp v148, v148, v148 row_bcast:31 row_mask:0xc bank_mask:0xf
	s_nop 0
	v_readlane_b32 s0, v148, 63
	s_nop 1
	v_mov_b32_e32 v148, s0
	v_fmamk_f32 v148, v148, 0x3b000000, v162
	v_mul_f32_e32 v150, 0x4b800000, v148
	v_cmp_gt_f32_e32 vcc, s31, v148
	s_nop 1
	v_cndmask_b32_e32 v148, v148, v150, vcc
	v_rsq_f32_e32 v148, v148
	s_nop 0
	v_mul_f32_e32 v150, 0x45800000, v148
	v_cndmask_b32_e32 v149, v148, v150, vcc
	v_mul_f32_e32 v140, v149, v140
	v_mul_f32_e32 v141, v149, v141
	v_mul_f32_e32 v142, v149, v142
	v_mul_f32_e32 v143, v149, v143
	v_mul_f32_e32 v144, v149, v144
	v_mul_f32_e32 v145, v149, v145
	v_mul_f32_e32 v146, v149, v146
	v_mul_f32_e32 v147, v149, v147
	v_cvt_pk_bf16_f32 v140, v140, v141
	v_cvt_pk_bf16_f32 v141, v142, v143
	v_cvt_pk_bf16_f32 v142, v144, v145
	v_cvt_pk_bf16_f32 v143, v146, v147
	global_store_dwordx4 v[156:157], v[140:143], off sc1
	s_waitcnt vmcnt(6)
; __device__ __forceinline__ unsigned cvt_pk_bf16(float lo, float hi) { unsigned r; asm volatile("v_cvt_pk_bf16_f32 %0, %1, %2" : "=v"(r) : "v"(lo), "v"(hi)); return r; }
; __device__ __forceinline__ float bf_lo(unsigned w) { return __uint_as_float(w << 16); }
; __device__ __forceinline__ float bf_hi(unsigned w) { return __uint_as_float(w & 0xffff0000u); }
; __global__ void __launch_bounds__(512, 2) trunk_fwd(Args args) {
;     ...
;             for (int ch = gw; ch < M / 16; ch += NGW) {
;     ...
;                 for (int rr = 0; rr < 16; ++rr) {
;                     const int r = r0 + rr;
;                     const u32x4 gb = gb_n, gu = gu_n; const f32x4 pv4 = pv_n;
;                     if (rr < 15) { gb_n = *(const u32x4*)(Z + (size_t)(r + 1) * INP + 768 + c0); gu_n = *(const u32x4*)(Z + (size_t)(r + 1) * INP + 1280 + c0);
;                                    pv_n = *(const f32x4*)(pl + (size_t)(r + 1) * PLE + lane * 4); }
;                     float cv[8], uu[8]; float ss = 0.f;
; #pragma unroll
;                     for (int i = 0; i < 4; ++i) {
;                         uu[2 * i] = bf_lo(gu[i]); uu[2 * i + 1] = bf_hi(gu[i]);
;                         cv[2 * i] = bf_lo(gb[i]) * (w0[2 * i] * uu[2 * i] + w1[2 * i] * u1[2 * i] + w2[2 * i] * u2[2 * i]);
;                         cv[2 * i + 1] = bf_hi(gb[i]) * (w0[2 * i + 1] * uu[2 * i + 1] + w1[2 * i + 1] * u1[2 * i + 1] + w2[2 * i + 1] * u2[2 * i + 1]);
;                     }
; #pragma unroll
;                     for (int i = 0; i < 8; ++i) { ss += cv[i] * cv[i]; u2[i] = u1[i]; u1[i] = uu[i]; }
;                     ss = wave_sum(ss);
;                     const float rc = rsqrtf(ss * (1.0f / 512.0f) + EPS);
;                     u32x4 oc;
; #pragma unroll
;                     for (int i = 0; i < 4; ++i) oc[i] = cvt_pk_bf16(cv[2 * i] * rc, cv[2 * i + 1] * rc);
;                     *(u32x4*)(MIX + (size_t)r * 1024 + 512 + c0) = oc;
	v_lshlrev_b32_e32 v188, 16, v30
	v_and_b32_e32 v189, 0xffff0000, v30
	v_lshlrev_b32_e32 v190, 16, v31
	v_and_b32_e32 v191, 0xffff0000, v31
	v_lshlrev_b32_e32 v192, 16, v32
	v_and_b32_e32 v193, 0xffff0000, v32
	v_lshlrev_b32_e32 v194, 16, v33
	v_and_b32_e32 v195, 0xffff0000, v33
	v_mul_f32_e32 v140, v164, v188
	v_mul_f32_e32 v141, v165, v189
	v_mul_f32_e32 v142, v166, v190
	v_mul_f32_e32 v143, v167, v191
	v_mul_f32_e32 v144, v168, v192
	v_mul_f32_e32 v145, v169, v193
	v_mul_f32_e32 v146, v170, v194
	v_mul_f32_e32 v147, v171, v195
	v_fmac_f32_e32 v140, v172, v204
	v_fmac_f32_e32 v141, v173, v205
	v_fmac_f32_e32 v142, v174, v206
	v_fmac_f32_e32 v143, v175, v207
	v_fmac_f32_e32 v144, v176, v208
	v_fmac_f32_e32 v145, v177, v209
	v_fmac_f32_e32 v146, v178, v210
	v_fmac_f32_e32 v147, v179, v211
	v_fmac_f32_e32 v140, v180, v196
	v_fmac_f32_e32 v141, v181, v197
	v_fmac_f32_e32 v142, v182, v198
	v_fmac_f32_e32 v143, v183, v199
	v_fmac_f32_e32 v144, v184, v200
	v_fmac_f32_e32 v145, v185, v201
	v_fmac_f32_e32 v146, v186, v202
	v_fmac_f32_e32 v147, v187, v203
	v_lshlrev_b32_e32 v150, 16, v14
	v_and_b32_e32 v151, 0xffff0000, v14
	v_mul_f32_e32 v140, v150, v140
	v_mul_f32_e32 v141, v151, v141
	v_lshlrev_b32_e32 v150, 16, v15
	v_and_b32_e32 v151, 0xffff0000, v15
	v_mul_f32_e32 v142, v150, v142
	v_mul_f32_e32 v143, v151, v143
	v_lshlrev_b32_e32 v150, 16, v16
	v_and_b32_e32 v151, 0xffff0000, v16
	v_mul_f32_e32 v144, v150, v144
	v_mul_f32_e32 v145, v151, v145
	v_lshlrev_b32_e32 v150, 16, v17
	v_and_b32_e32 v151, 0xffff0000, v17
	v_mul_f32_e32 v146, v150, v146
	v_mul_f32_e32 v147, v151, v147
	v_mul_f32_e32 v148, v140, v140
	v_fmac_f32_e32 v148, v141, v141
	v_fmac_f32_e32 v148, v142, v142
	v_fmac_f32_e32 v148, v143, v143
	v_fmac_f32_e32 v148, v144, v144
	v_fmac_f32_e32 v148, v145, v145
	v_fmac_f32_e32 v148, v146, v146
	v_fmac_f32_e32 v148, v147, v147
	s_nop 1
	v_add_f32_dpp v148, v148, v148 quad_perm:[1,0,3,2] row_mask:0xf bank_mask:0xf
	s_nop 1
	v_add_f32_dpp v148, v148, v148 quad_perm:[2,3,0,1] row_mask:0xf bank_mask:0xf
	s_nop 1
	v_add_f32_dpp v148, v148, v148 row_half_mirror row_mask:0xf bank_mask:0xf
	s_nop 1
	v_add_f32_dpp v148, v148, v148 row_mirror row_mask:0xf bank_mask:0xf
	s_nop 1
	v_add_f32_dpp v148, v148, v148 row_bcast:15 row_mask:0xa bank_mask:0xf
	s_nop 1
	v_add_f32_dpp v148, v148, v148 row_bcast:31 row_mask:0xc bank_mask:0xf
	s_nop 0
	v_readlane_b32 s0, v148, 63
	s_nop 1
	v_mov_b32_e32 v148, s0
	v_fmamk_f32 v148, v148, 0x3b000000, v162
	v_mul_f32_e32 v150, 0x4b800000, v148
	v_cmp_gt_f32_e32 vcc, s31, v148
	s_nop 1
	v_cndmask_b32_e32 v148, v148, v150, vcc
	v_rsq_f32_e32 v148, v148
	s_nop 0
	v_mul_f32_e32 v150, 0x45800000, v148
	v_cndmask_b32_e32 v149, v148, v150, vcc
	v_mul_f32_e32 v140, v149, v140
	v_mul_f32_e32 v141, v149, v141
	v_mul_f32_e32 v142, v149, v142
	v_mul_f32_e32 v143, v149, v143
	v_mul_f32_e32 v144, v149, v144
	v_mul_f32_e32 v145, v149, v145
	v_mul_f32_e32 v146, v149, v146
	v_mul_f32_e32 v147, v149, v147
	v_cvt_pk_bf16_f32 v140, v140, v141
	v_cvt_pk_bf16_f32 v141, v142, v143
	v_cvt_pk_bf16_f32 v142, v144, v145
	v_cvt_pk_bf16_f32 v143, v146, v147
	global_store_dwordx4 v[156:157], v[140:143], off offset:2048 sc1
	v_lshl_add_u64 v[156:157], v[156:157], 0, s[20:21]
	s_branch .LBB0_1053
